# v2 + QKV and gMLP-in epilogues: the eight serialized row-statistics loads batched behind one wait
# baseline (speedup 1.0000x reference)
; __device__ __forceinline__ float rstd_of(float ss) { return __builtin_amdgcn_rsqf(ss * (1.0f / 2048.0f) + NORM_EPS); }
;     __device__ __forceinline__ void operator()(const f32x4 (&acc)[2][2][4][2], const Unit& u, int wr, int wc, int fr, int fq) const {
;         const int rt = wr * 64 + fr, which = u.pn >> 3, colt = (u.pn & 7) * BM + wc * 32 + 4 * fq;
;         float rs[2][4];
; #pragma unroll
;         for (int ai = 0; ai < 2; ++ai)
; #pragma unroll
;             for (int m = 0; m < 4; ++m) rs[ai][m] = rstd_of(ss[u.pm * BM + ai * HALF + m * 16 + rt]);
.LBB0_87:
	v_lshl_add_u32 v150, s2, 8, v143
	v_ashrrev_i32_e32 v151, 31, v150
	v_lshl_add_u64 v[136:137], v[150:151], 2, s[12:13]
	global_load_dword v152, v[136:137], off
	global_load_dword v148, v[136:137], off offset:64
	global_load_dword v146, v[136:137], off offset:128
	global_load_dword v144, v[136:137], off offset:192
	global_load_dword v142, v[136:137], off offset:512
	global_load_dword v140, v[136:137], off offset:576
	global_load_dword v138, v[136:137], off offset:640
	global_load_dword v136, v[136:137], off offset:704
	s_lshl_b32 s19, s6, 8
	s_and_b32 s19, s19, 0x700
	s_or_b32 s19, s19, s56
	v_add_u32_e32 v154, s19, v147
	s_mov_b64 s[86:87], -1
	s_cmp_gt_u32 s6, 7
	s_waitcnt vmcnt(0)
	v_fmamk_f32 v152, v152, 0x3a000000, v153
	v_fmamk_f32 v148, v148, 0x3a000000, v153
	v_fmamk_f32 v146, v146, 0x3a000000, v153
	v_fmamk_f32 v144, v144, 0x3a000000, v153
	v_fmamk_f32 v142, v142, 0x3a000000, v153
	v_fmamk_f32 v140, v140, 0x3a000000, v153
	v_fmamk_f32 v138, v138, 0x3a000000, v153
	v_fmamk_f32 v136, v136, 0x3a000000, v153
	v_rsq_f32_e32 v152, v152
	v_rsq_f32_e32 v148, v148
	v_rsq_f32_e32 v146, v146
	v_rsq_f32_e32 v144, v144
	v_rsq_f32_e32 v142, v142
	v_rsq_f32_e32 v140, v140
	v_rsq_f32_e32 v138, v138
	v_rsq_f32_e32 v136, v136
	s_cbranch_scc1 .LBB0_92
	s_and_b64 vcc, exec, s[86:87]
	s_cbranch_vccnz .LBB0_97

; __device__ __forceinline__ unsigned cvt_pk_bf16(float lo, float hi) { unsigned r; asm volatile("v_cvt_pk_bf16_f32 %0, %1, %2" : "=v"(r) : "v"(lo), "v"(hi)); return r; }
; __device__ __forceinline__ float rstd_of(float ss) { return __builtin_amdgcn_rsqf(ss * (1.0f / 2048.0f) + NORM_EPS); }
; __device__ __forceinline__ float gelu_tanh(float x) { const float u = x * (1.5957691216057308f + 0.0713548162726009f * x * x); return x * sigmoid_f(u); }
;     __device__ __forceinline__ void operator()(const f32x4 (&acc)[2][2][4][2], const Unit& u, int wr, int wc, int fr, int fq) const {
;         const int rt = wr * 64 + fr, isv = u.pn >> 3, col0 = (u.pn & 7) * BM + wc * 32 + 8 * fq;
;         bf16_t* base = (isv ? V : U) + (size_t)(u.pm * BM + rt) * LD + col0;
; #pragma unroll
;         for (int ai = 0; ai < 2; ++ai)
; #pragma unroll
;             for (int m = 0; m < 4; ++m) { bf16_t* rowp = base + (size_t)(ai * HALF + m * 16) * LD; const int grow = u.pm * BM + ai * HALF + m * 16 + rt; const float rs = rstd_of(ssin[grow]); float sq = 0.f;
; #pragma unroll
;                 for (int bj = 0; bj < 2; ++bj) { f32x4 v0 = acc[ai][bj][m][0] * rs, v1 = acc[ai][bj][m][1] * rs;
; #pragma unroll
;                     for (int j = 0; j < 4; ++j) { v0[j] = gelu_tanh(v0[j]); v1[j] = gelu_tanh(v1[j]); }
;                     sq += (v0[0] * v0[0] + v0[1] * v0[1]) + (v0[2] * v0[2] + v0[3] * v0[3]) + (v1[0] * v1[0] + v1[1] * v1[1]) + (v1[2] * v1[2] + v1[3] * v1[3]);
;                     u32x4 w; w.x = cvt_pk_bf16(v0[0], v0[1]); w.y = cvt_pk_bf16(v0[2], v0[3]); w.z = cvt_pk_bf16(v1[0], v1[1]); w.w = cvt_pk_bf16(v1[2], v1[3]);
;                     *(u32x4*)(rowp + bj * HALF) = w; }
.LBB0_797:
	s_lshl_b32 s0, s14, 8
	s_and_b32 s0, s0, 0x700
	s_cmp_gt_u32 s14, 7
	v_add_u32_e32 v128, s0, v161
	s_cselect_b64 s[0:1], -1, 0
	s_cmp_lt_u32 s14, 8
	s_cselect_b64 s[6:7], -1, 0
	s_and_b64 vcc, s[6:7], exec
	s_cselect_b32 s7, s9, s11
	s_cselect_b32 s6, s8, s10
	s_lshl_b32 s16, s54, 8
	v_add_u32_e32 v148, s16, v159
	v_ashrrev_i32_e32 v149, 31, v148
	v_lshlrev_b64 v[130:131], 12, v[148:149]
	v_lshl_add_u64 v[130:131], s[6:7], 0, v[130:131]
	v_ashrrev_i32_e32 v129, 31, v128
	v_lshl_add_u64 v[146:147], v[128:129], 1, v[130:131]
	v_lshl_add_u64 v[128:129], v[148:149], 2, s[66:67]
	global_load_dword v226, v[128:129], off
	global_load_dword v227, v[128:129], off offset:64
	global_load_dword v228, v[128:129], off offset:128
	global_load_dword v229, v[128:129], off offset:192
	global_load_dword v230, v[128:129], off offset:512
	global_load_dword v231, v[128:129], off offset:576
	global_load_dword v232, v[128:129], off offset:640
	global_load_dword v233, v[128:129], off offset:704
	s_waitcnt vmcnt(0)
	v_mov_b32_e32 v128, v226
	v_fmamk_f32 v128, v128, 0x3a000000, v166
	v_rsq_f32_e32 v138, v128
	s_nop 0
	v_pk_mul_f32 v[130:131], v[124:125], v[138:139] op_sel_hi:[1,0]
	s_nop 0
	v_mul_f32_e32 v154, 0x3d922279, v130
	v_fmaak_f32 v154, v130, v154, 0x3fcc422a
	v_mul_f32_e32 v154, v130, v154
	v_mul_f32_e32 v154, 0xbfb8aa3b, v154
	v_exp_f32_e32 v154, v154
	v_pk_mul_f32 v[152:153], v[120:121], v[138:139] op_sel_hi:[1,0]
	v_pk_mul_f32 v[128:129], v[126:127], v[138:139] op_sel_hi:[1,0]
	v_pk_mul_f32 v[150:151], v[122:123], v[138:139] op_sel_hi:[1,0]
	v_add_f32_e32 v154, 1.0, v154
	v_rcp_f32_e32 v154, v154
	s_nop 0
	v_mul_f32_e32 v154, v130, v154
	v_mul_f32_e32 v130, 0x3d922279, v152
	v_fmaak_f32 v130, v152, v130, 0x3fcc422a
	v_mul_f32_e32 v130, v152, v130
	v_mul_f32_e32 v130, 0xbfb8aa3b, v130
	v_exp_f32_e32 v130, v130
	s_nop 0
	v_add_f32_e32 v130, 1.0, v130
	v_rcp_f32_e32 v130, v130
	s_nop 0
	v_mul_f32_e32 v155, v152, v130
	v_mul_f32_e32 v130, 0x3d922279, v131
	v_fmaak_f32 v130, v131, v130, 0x3fcc422a
	v_mul_f32_e32 v130, v131, v130
	v_mul_f32_e32 v130, 0xbfb8aa3b, v130
	v_exp_f32_e32 v130, v130
	s_nop 0
	v_add_f32_e32 v130, 1.0, v130
	v_rcp_f32_e32 v130, v130
	s_nop 0
	v_mul_f32_e32 v156, v131, v130
	v_mul_f32_e32 v130, 0x3d922279, v153
	v_fmaak_f32 v130, v153, v130, 0x3fcc422a
	v_mul_f32_e32 v130, v153, v130
	v_mul_f32_e32 v130, 0xbfb8aa3b, v130
	v_exp_f32_e32 v130, v130
	s_nop 0
	v_add_f32_e32 v130, 1.0, v130
	v_rcp_f32_e32 v130, v130
	s_nop 0
	v_mul_f32_e32 v157, v153, v130
	v_mul_f32_e32 v130, 0x3d922279, v128
	v_fmaak_f32 v130, v128, v130, 0x3fcc422a
	v_mul_f32_e32 v130, v128, v130
	v_mul_f32_e32 v130, 0xbfb8aa3b, v130
	v_exp_f32_e32 v130, v130
	v_pk_mul_f32 v[152:153], v[92:93], v[138:139] op_sel_hi:[1,0]
	v_add_f32_e32 v130, 1.0, v130
	v_rcp_f32_e32 v130, v130
	s_nop 0
	v_mul_f32_e32 v167, v128, v130
	v_mul_f32_e32 v128, 0x3d922279, v150
	v_fmaak_f32 v128, v150, v128, 0x3fcc422a
	v_mul_f32_e32 v128, v150, v128
	v_mul_f32_e32 v128, 0xbfb8aa3b, v128
	v_exp_f32_e32 v128, v128
	s_nop 0
	v_add_f32_e32 v128, 1.0, v128
	v_rcp_f32_e32 v128, v128
	s_nop 0
	v_mul_f32_e32 v168, v150, v128
	v_mul_f32_e32 v128, 0x3d922279, v129
	v_fmaak_f32 v128, v129, v128, 0x3fcc422a
	v_mul_f32_e32 v128, v129, v128
	v_mul_f32_e32 v128, 0xbfb8aa3b, v128
	v_exp_f32_e32 v128, v128
	s_nop 0
	v_add_f32_e32 v128, 1.0, v128
	v_rcp_f32_e32 v128, v128
	s_nop 0
	v_mul_f32_e32 v169, v129, v128
	v_mul_f32_e32 v128, 0x3d922279, v151
	v_fmaak_f32 v128, v151, v128, 0x3fcc422a
	v_mul_f32_e32 v128, v151, v128
	v_mul_f32_e32 v128, 0xbfb8aa3b, v128
	v_exp_f32_e32 v128, v128
	s_nop 0
	v_add_f32_e32 v128, 1.0, v128
	v_rcp_f32_e32 v128, v128
	s_nop 0
	v_mul_f32_e32 v170, v151, v128
	v_cvt_pk_bf16_f32 v128, v154, v156
	v_cvt_pk_bf16_f32 v129, v167, v169
	v_cvt_pk_bf16_f32 v130, v155, v157
	v_cvt_pk_bf16_f32 v131, v168, v170
	global_store_dwordx4 v[146:147], v[128:131], off
	v_pk_mul_f32 v[150:151], v[88:89], v[138:139] op_sel_hi:[1,0]
	s_nop 0
	v_pk_mul_f32 v[130:131], v[94:95], v[138:139] op_sel_hi:[1,0]
	v_pk_mul_f32 v[128:129], v[90:91], v[138:139] op_sel_hi:[1,0]
	v_mul_f32_e32 v138, 0x3d922279, v152
	v_fmaak_f32 v138, v152, v138, 0x3fcc422a
	v_mul_f32_e32 v138, v152, v138
	v_mul_f32_e32 v138, 0xbfb8aa3b, v138
	v_exp_f32_e32 v138, v138
	s_nop 0
	v_add_f32_e32 v138, 1.0, v138
	v_rcp_f32_e32 v138, v138
	s_nop 0
	v_mul_f32_e32 v138, v152, v138
	v_mul_f32_e32 v152, 0x3d922279, v150
	v_fmaak_f32 v152, v150, v152, 0x3fcc422a
	v_mul_f32_e32 v152, v150, v152
	v_mul_f32_e32 v152, 0xbfb8aa3b, v152
	v_exp_f32_e32 v152, v152
	s_nop 0
	v_add_f32_e32 v152, 1.0, v152
	v_rcp_f32_e32 v152, v152
	s_nop 0
	v_mul_f32_e32 v150, v150, v152
	v_mul_f32_e32 v152, 0x3d922279, v153
	v_fmaak_f32 v152, v153, v152, 0x3fcc422a
	v_mul_f32_e32 v152, v153, v152
	v_mul_f32_e32 v152, 0xbfb8aa3b, v152
	v_exp_f32_e32 v152, v152
	s_nop 0
	v_add_f32_e32 v152, 1.0, v152
	v_rcp_f32_e32 v152, v152
	s_nop 0
	v_mul_f32_e32 v152, v153, v152
	v_mul_f32_e32 v153, 0x3d922279, v151
	v_fmaak_f32 v153, v151, v153, 0x3fcc422a
	v_mul_f32_e32 v153, v151, v153
	v_mul_f32_e32 v153, 0xbfb8aa3b, v153
	v_exp_f32_e32 v153, v153
	v_cvt_pk_bf16_f32 v172, v138, v152
	s_nop 0
	v_add_f32_e32 v153, 1.0, v153
	v_rcp_f32_e32 v153, v153
	s_nop 0
	v_mul_f32_e32 v151, v151, v153
	v_mul_f32_e32 v153, 0x3d922279, v130
	v_fmaak_f32 v153, v130, v153, 0x3fcc422a
	v_mul_f32_e32 v153, v130, v153
	v_mul_f32_e32 v153, 0xbfb8aa3b, v153
	v_exp_f32_e32 v153, v153
	s_nop 0
	v_add_f32_e32 v153, 1.0, v153
	v_rcp_f32_e32 v153, v153
	s_nop 0
	v_mul_f32_e32 v130, v130, v153
	v_mul_f32_e32 v153, 0x3d922279, v128
	v_fmaak_f32 v153, v128, v153, 0x3fcc422a
	v_mul_f32_e32 v153, v128, v153
	v_mul_f32_e32 v153, 0xbfb8aa3b, v153
	v_exp_f32_e32 v153, v153
	s_nop 0
	v_add_f32_e32 v153, 1.0, v153
	v_rcp_f32_e32 v153, v153
	s_nop 0
	v_mul_f32_e32 v128, v128, v153
	v_mul_f32_e32 v153, 0x3d922279, v131
	v_fmaak_f32 v153, v131, v153, 0x3fcc422a
	v_mul_f32_e32 v153, v131, v153
	v_mul_f32_e32 v153, 0xbfb8aa3b, v153
	v_exp_f32_e32 v153, v153
	s_nop 0
	v_add_f32_e32 v153, 1.0, v153
	v_rcp_f32_e32 v153, v153
	s_nop 0
	v_mul_f32_e32 v131, v131, v153
	v_mul_f32_e32 v153, 0x3d922279, v129
	v_fmaak_f32 v153, v129, v153, 0x3fcc422a
	v_mul_f32_e32 v153, v129, v153
	v_mul_f32_e32 v153, 0xbfb8aa3b, v153
	v_exp_f32_e32 v153, v153
	v_cvt_pk_bf16_f32 v173, v130, v131
	v_cvt_pk_bf16_f32 v174, v150, v151
	s_nop 0
	v_add_f32_e32 v153, 1.0, v153
	v_rcp_f32_e32 v153, v153
	s_nop 0
	v_mul_f32_e32 v129, v129, v153
	v_cvt_pk_bf16_f32 v175, v128, v129
	global_store_dwordx4 v[146:147], v[172:175], off offset:256
	s_cbranch_vccnz .LBB0_801
; __device__ __forceinline__ unsigned cvt_pk_bf16(float lo, float hi) { unsigned r; asm volatile("v_cvt_pk_bf16_f32 %0, %1, %2" : "=v"(r) : "v"(lo), "v"(hi)); return r; }
;     __device__ __forceinline__ void operator()(const f32x4 (&acc)[2][2][4][2], const Unit& u, int wr, int wc, int fr, int fq) const {
;     ...
;                     sq += (v0[0] * v0[0] + v0[1] * v0[1]) + (v0[2] * v0[2] + v0[3] * v0[3]) + (v1[0] * v1[0] + v1[1] * v1[1]) + (v1[2] * v1[2] + v1[3] * v1[3]);
;                     u32x4 w; w.x = cvt_pk_bf16(v0[0], v0[1]); w.y = cvt_pk_bf16(v0[2], v0[3]); w.z = cvt_pk_bf16(v1[0], v1[1]); w.w = cvt_pk_bf16(v1[2], v1[3]);
;                     *(u32x4*)(rowp + bj * HALF) = w; }
;                 if (isv) { sq += __shfl_xor(sq, 16); sq += __shfl_xor(sq, 32); if (fq == 0) unsafeAtomicAdd(ssv + grow, sq); } }
	v_mul_f32_e32 v156, v156, v156
	v_fmac_f32_e32 v156, v154, v154
	v_mul_f32_e32 v154, v169, v169
	v_mul_f32_e32 v129, v129, v129
	v_fmac_f32_e32 v154, v167, v167
	v_fmac_f32_e32 v129, v128, v128
	v_mul_f32_e32 v128, v152, v152
	v_mul_f32_e32 v131, v131, v131
	v_add_f32_e32 v154, v156, v154
	v_mul_f32_e32 v156, v157, v157
	v_fmac_f32_e32 v128, v138, v138
	v_fmac_f32_e32 v131, v130, v130
	v_mul_f32_e32 v130, v151, v151
	v_mul_f32_e32 v153, v170, v170
	v_fmac_f32_e32 v156, v155, v155
	v_add_f32_e32 v128, v128, v131
	v_fmac_f32_e32 v130, v150, v150
	v_fmac_f32_e32 v153, v168, v168
	v_add_f32_e32 v154, v156, v154
	v_add_f32_e32 v128, v130, v128
	v_add_f32_e32 v153, v153, v154
	v_add_f32_e32 v128, v129, v128
	v_add_f32_e32 v128, v153, v128
	ds_bpermute_b32 v129, v162, v128
	s_waitcnt lgkmcnt(0)
	v_add_f32_e32 v128, v128, v129
	ds_bpermute_b32 v129, v163, v128
	s_and_saveexec_b64 s[6:7], s[4:5]
	s_cbranch_execz .LBB0_800
	v_lshl_add_u64 v[130:131], v[148:149], 2, s[68:69]
	s_waitcnt lgkmcnt(0)
	v_add_f32_e32 v128, v128, v129
	global_atomic_add_f32 v[130:131], v128, off

; __device__ __forceinline__ unsigned cvt_pk_bf16(float lo, float hi) { unsigned r; asm volatile("v_cvt_pk_bf16_f32 %0, %1, %2" : "=v"(r) : "v"(lo), "v"(hi)); return r; }
; __device__ __forceinline__ float rstd_of(float ss) { return __builtin_amdgcn_rsqf(ss * (1.0f / 2048.0f) + NORM_EPS); }
; __device__ __forceinline__ float gelu_tanh(float x) { const float u = x * (1.5957691216057308f + 0.0713548162726009f * x * x); return x * sigmoid_f(u); }
;     __device__ __forceinline__ void operator()(const f32x4 (&acc)[2][2][4][2], const Unit& u, int wr, int wc, int fr, int fq) const {
;     ...
;             for (int m = 0; m < 4; ++m) { bf16_t* rowp = base + (size_t)(ai * HALF + m * 16) * LD; const int grow = u.pm * BM + ai * HALF + m * 16 + rt; const float rs = rstd_of(ssin[grow]); float sq = 0.f;
; #pragma unroll
;                 for (int bj = 0; bj < 2; ++bj) { f32x4 v0 = acc[ai][bj][m][0] * rs, v1 = acc[ai][bj][m][1] * rs;
; #pragma unroll
;                     for (int j = 0; j < 4; ++j) { v0[j] = gelu_tanh(v0[j]); v1[j] = gelu_tanh(v1[j]); }
;                     sq += (v0[0] * v0[0] + v0[1] * v0[1]) + (v0[2] * v0[2] + v0[3] * v0[3]) + (v1[0] * v1[0] + v1[1] * v1[1]) + (v1[2] * v1[2] + v1[3] * v1[3]);
;                     u32x4 w; w.x = cvt_pk_bf16(v0[0], v0[1]); w.y = cvt_pk_bf16(v0[2], v0[3]); w.z = cvt_pk_bf16(v1[0], v1[1]); w.w = cvt_pk_bf16(v1[2], v1[3]);
;                     *(u32x4*)(rowp + bj * HALF) = w; }
;                 if (isv) { sq += __shfl_xor(sq, 16); sq += __shfl_xor(sq, 32); if (fq == 0) unsafeAtomicAdd(ssv + grow, sq); } }
.LBB0_801:
	v_or_b32_e32 v150, 16, v148
	v_ashrrev_i32_e32 v151, 31, v150
	s_waitcnt lgkmcnt(0)
	v_lshl_add_u64 v[128:129], v[150:151], 2, s[66:67]
	v_mov_b32_e32 v128, v227
	s_mov_b32 s6, 0x10000
	v_fmamk_f32 v128, v128, 0x3a000000, v166
	v_rsq_f32_e32 v138, v128
	s_nop 0
	v_pk_mul_f32 v[130:131], v[116:117], v[138:139] op_sel_hi:[1,0]
	s_nop 0
	v_mul_f32_e32 v149, 0x3d922279, v130
	v_fmaak_f32 v149, v130, v149, 0x3fcc422a
	v_mul_f32_e32 v149, v130, v149
	v_mul_f32_e32 v149, 0xbfb8aa3b, v149
	v_exp_f32_e32 v149, v149
	v_pk_mul_f32 v[154:155], v[112:113], v[138:139] op_sel_hi:[1,0]
	v_pk_mul_f32 v[128:129], v[118:119], v[138:139] op_sel_hi:[1,0]
	v_pk_mul_f32 v[152:153], v[114:115], v[138:139] op_sel_hi:[1,0]
	v_add_f32_e32 v149, 1.0, v149
	v_rcp_f32_e32 v149, v149
	v_pk_mul_f32 v[156:157], v[84:85], v[138:139] op_sel_hi:[1,0]
	v_mul_f32_e32 v149, v130, v149
	v_mul_f32_e32 v130, 0x3d922279, v154
	v_fmaak_f32 v130, v154, v130, 0x3fcc422a
	v_mul_f32_e32 v130, v154, v130
	v_mul_f32_e32 v130, 0xbfb8aa3b, v130
	v_exp_f32_e32 v130, v130
	s_nop 0
	v_add_f32_e32 v130, 1.0, v130
	v_rcp_f32_e32 v130, v130
	s_nop 0
	v_mul_f32_e32 v167, v154, v130
	v_mul_f32_e32 v130, 0x3d922279, v131
	v_fmaak_f32 v130, v131, v130, 0x3fcc422a
	v_mul_f32_e32 v130, v131, v130
	v_mul_f32_e32 v130, 0xbfb8aa3b, v130
	v_exp_f32_e32 v130, v130
	s_nop 0
	v_add_f32_e32 v130, 1.0, v130
	v_rcp_f32_e32 v130, v130
	s_nop 0
	v_mul_f32_e32 v168, v131, v130
	v_mul_f32_e32 v130, 0x3d922279, v155
	v_fmaak_f32 v130, v155, v130, 0x3fcc422a
	v_mul_f32_e32 v130, v155, v130
	v_mul_f32_e32 v130, 0xbfb8aa3b, v130
	v_exp_f32_e32 v130, v130
	s_nop 0
	v_add_f32_e32 v130, 1.0, v130
	v_rcp_f32_e32 v130, v130
	s_nop 0
	v_mul_f32_e32 v169, v155, v130
	v_mul_f32_e32 v130, 0x3d922279, v128
	v_fmaak_f32 v130, v128, v130, 0x3fcc422a
	v_mul_f32_e32 v130, v128, v130
	v_mul_f32_e32 v130, 0xbfb8aa3b, v130
	v_exp_f32_e32 v130, v130
	v_pk_mul_f32 v[154:155], v[80:81], v[138:139] op_sel_hi:[1,0]
	v_add_f32_e32 v130, 1.0, v130
	v_rcp_f32_e32 v130, v130
	s_nop 0
	v_mul_f32_e32 v170, v128, v130
	v_mul_f32_e32 v128, 0x3d922279, v152
	v_fmaak_f32 v128, v152, v128, 0x3fcc422a
	v_mul_f32_e32 v128, v152, v128
	v_mul_f32_e32 v128, 0xbfb8aa3b, v128
	v_exp_f32_e32 v128, v128
	s_nop 0
	v_add_f32_e32 v128, 1.0, v128
	v_rcp_f32_e32 v128, v128
	s_nop 0
	v_mul_f32_e32 v171, v152, v128
	v_mul_f32_e32 v128, 0x3d922279, v129
	v_fmaak_f32 v128, v129, v128, 0x3fcc422a
	v_mul_f32_e32 v128, v129, v128
	v_mul_f32_e32 v128, 0xbfb8aa3b, v128
	v_exp_f32_e32 v128, v128
	v_add_co_u32_e32 v152, vcc, s6, v146
	v_add_f32_e32 v128, 1.0, v128
	v_rcp_f32_e32 v128, v128
	s_nop 0
	v_mul_f32_e32 v172, v129, v128
	v_mul_f32_e32 v128, 0x3d922279, v153
	v_fmaak_f32 v128, v153, v128, 0x3fcc422a
	v_mul_f32_e32 v128, v153, v128
	v_mul_f32_e32 v128, 0xbfb8aa3b, v128
	v_exp_f32_e32 v128, v128
	s_nop 0
	v_add_f32_e32 v128, 1.0, v128
	v_rcp_f32_e32 v128, v128
	s_nop 0
	v_mul_f32_e32 v173, v153, v128
	v_cvt_pk_bf16_f32 v128, v149, v168
	v_cvt_pk_bf16_f32 v129, v170, v172
	v_cvt_pk_bf16_f32 v130, v167, v169
	v_cvt_pk_bf16_f32 v131, v171, v173
	v_addc_co_u32_e32 v153, vcc, 0, v147, vcc
	global_store_dwordx4 v[152:153], v[128:131], off
	s_andn2_b64 vcc, exec, s[0:1]
	s_nop 0
	v_pk_mul_f32 v[130:131], v[86:87], v[138:139] op_sel_hi:[1,0]
	v_pk_mul_f32 v[128:129], v[82:83], v[138:139] op_sel_hi:[1,0]
	v_mul_f32_e32 v138, 0x3d922279, v156
	v_fmaak_f32 v138, v156, v138, 0x3fcc422a
	v_mul_f32_e32 v138, v156, v138
	v_mul_f32_e32 v138, 0xbfb8aa3b, v138
	v_exp_f32_e32 v138, v138
	s_nop 0
	v_add_f32_e32 v138, 1.0, v138
	v_rcp_f32_e32 v138, v138
	s_nop 0
	v_mul_f32_e32 v138, v156, v138
	v_mul_f32_e32 v156, 0x3d922279, v154
	v_fmaak_f32 v156, v154, v156, 0x3fcc422a
	v_mul_f32_e32 v156, v154, v156
	v_mul_f32_e32 v156, 0xbfb8aa3b, v156
	v_exp_f32_e32 v156, v156
	s_nop 0
	v_add_f32_e32 v156, 1.0, v156
	v_rcp_f32_e32 v156, v156
	s_nop 0
	v_mul_f32_e32 v154, v154, v156
	v_mul_f32_e32 v156, 0x3d922279, v157
	v_fmaak_f32 v156, v157, v156, 0x3fcc422a
	v_mul_f32_e32 v156, v157, v156
	v_mul_f32_e32 v156, 0xbfb8aa3b, v156
	v_exp_f32_e32 v156, v156
	s_nop 0
	v_add_f32_e32 v156, 1.0, v156
	v_rcp_f32_e32 v156, v156
	s_nop 0
	v_mul_f32_e32 v156, v157, v156
	v_mul_f32_e32 v157, 0x3d922279, v155
	v_fmaak_f32 v157, v155, v157, 0x3fcc422a
	v_mul_f32_e32 v157, v155, v157
	v_mul_f32_e32 v157, 0xbfb8aa3b, v157
	v_exp_f32_e32 v157, v157
	v_cvt_pk_bf16_f32 v174, v138, v156
	s_nop 0
	v_add_f32_e32 v157, 1.0, v157
	v_rcp_f32_e32 v157, v157
	s_nop 0
	v_mul_f32_e32 v155, v155, v157
	v_mul_f32_e32 v157, 0x3d922279, v130
	v_fmaak_f32 v157, v130, v157, 0x3fcc422a
	v_mul_f32_e32 v157, v130, v157
	v_mul_f32_e32 v157, 0xbfb8aa3b, v157
	v_exp_f32_e32 v157, v157
	s_nop 0
	v_add_f32_e32 v157, 1.0, v157
	v_rcp_f32_e32 v157, v157
	s_nop 0
	v_mul_f32_e32 v130, v130, v157
	v_mul_f32_e32 v157, 0x3d922279, v128
	v_fmaak_f32 v157, v128, v157, 0x3fcc422a
	v_mul_f32_e32 v157, v128, v157
	v_mul_f32_e32 v157, 0xbfb8aa3b, v157
	v_exp_f32_e32 v157, v157
	s_nop 0
	v_add_f32_e32 v157, 1.0, v157
	v_rcp_f32_e32 v157, v157
	s_nop 0
	v_mul_f32_e32 v128, v128, v157
	v_mul_f32_e32 v157, 0x3d922279, v131
	v_fmaak_f32 v157, v131, v157, 0x3fcc422a
	v_mul_f32_e32 v157, v131, v157
	v_mul_f32_e32 v157, 0xbfb8aa3b, v157
	v_exp_f32_e32 v157, v157
	s_nop 0
	v_add_f32_e32 v157, 1.0, v157
	v_rcp_f32_e32 v157, v157
	s_nop 0
	v_mul_f32_e32 v131, v131, v157
	v_mul_f32_e32 v157, 0x3d922279, v129
	v_fmaak_f32 v157, v129, v157, 0x3fcc422a
	v_mul_f32_e32 v157, v129, v157
	v_mul_f32_e32 v157, 0xbfb8aa3b, v157
	v_exp_f32_e32 v157, v157
	v_cvt_pk_bf16_f32 v175, v130, v131
	v_cvt_pk_bf16_f32 v176, v154, v155
	s_nop 0
	v_add_f32_e32 v157, 1.0, v157
	v_rcp_f32_e32 v157, v157
	s_nop 0
	v_mul_f32_e32 v129, v129, v157
	v_cvt_pk_bf16_f32 v177, v128, v129
	global_store_dwordx4 v[152:153], v[174:177], off offset:256
	v_cndmask_b32_e64 v152, 0, 1, s[0:1]
	v_cmp_ne_u32_e64 s[6:7], 1, v152
	s_cbranch_vccnz .LBB0_805
	v_mul_f32_e32 v153, v168, v168
	v_fmac_f32_e32 v153, v149, v149
	v_mul_f32_e32 v149, v172, v172
	v_mul_f32_e32 v129, v129, v129
	v_fmac_f32_e32 v149, v170, v170
	v_fmac_f32_e32 v129, v128, v128
	v_mul_f32_e32 v128, v156, v156
	v_mul_f32_e32 v131, v131, v131
	v_add_f32_e32 v149, v153, v149
	v_mul_f32_e32 v153, v169, v169
	v_fmac_f32_e32 v128, v138, v138
	v_fmac_f32_e32 v131, v130, v130
	v_mul_f32_e32 v130, v155, v155
	v_mul_f32_e32 v152, v173, v173
	v_fmac_f32_e32 v153, v167, v167
	v_add_f32_e32 v128, v128, v131
	v_fmac_f32_e32 v130, v154, v154
	v_fmac_f32_e32 v152, v171, v171
	v_add_f32_e32 v149, v153, v149
	v_add_f32_e32 v128, v130, v128
	v_add_f32_e32 v149, v152, v149
	v_add_f32_e32 v128, v129, v128
	v_add_f32_e32 v128, v149, v128
	ds_bpermute_b32 v129, v162, v128
	s_waitcnt lgkmcnt(0)
	v_add_f32_e32 v128, v128, v129
	ds_bpermute_b32 v129, v163, v128
	s_and_saveexec_b64 s[0:1], s[4:5]
	s_cbranch_execz .LBB0_804
	v_lshl_add_u64 v[130:131], v[150:151], 2, s[68:69]
	s_waitcnt lgkmcnt(0)
	v_add_f32_e32 v128, v128, v129
	global_atomic_add_f32 v[130:131], v128, off

; __device__ __forceinline__ unsigned cvt_pk_bf16(float lo, float hi) { unsigned r; asm volatile("v_cvt_pk_bf16_f32 %0, %1, %2" : "=v"(r) : "v"(lo), "v"(hi)); return r; }
; __device__ __forceinline__ float rstd_of(float ss) { return __builtin_amdgcn_rsqf(ss * (1.0f / 2048.0f) + NORM_EPS); }
; __device__ __forceinline__ float gelu_tanh(float x) { const float u = x * (1.5957691216057308f + 0.0713548162726009f * x * x); return x * sigmoid_f(u); }
;     __device__ __forceinline__ void operator()(const f32x4 (&acc)[2][2][4][2], const Unit& u, int wr, int wc, int fr, int fq) const {
;     ...
;             for (int m = 0; m < 4; ++m) { bf16_t* rowp = base + (size_t)(ai * HALF + m * 16) * LD; const int grow = u.pm * BM + ai * HALF + m * 16 + rt; const float rs = rstd_of(ssin[grow]); float sq = 0.f;
; #pragma unroll
;                 for (int bj = 0; bj < 2; ++bj) { f32x4 v0 = acc[ai][bj][m][0] * rs, v1 = acc[ai][bj][m][1] * rs;
; #pragma unroll
;                     for (int j = 0; j < 4; ++j) { v0[j] = gelu_tanh(v0[j]); v1[j] = gelu_tanh(v1[j]); }
;                     sq += (v0[0] * v0[0] + v0[1] * v0[1]) + (v0[2] * v0[2] + v0[3] * v0[3]) + (v1[0] * v1[0] + v1[1] * v1[1]) + (v1[2] * v1[2] + v1[3] * v1[3]);
;                     u32x4 w; w.x = cvt_pk_bf16(v0[0], v0[1]); w.y = cvt_pk_bf16(v0[2], v0[3]); w.z = cvt_pk_bf16(v1[0], v1[1]); w.w = cvt_pk_bf16(v1[2], v1[3]);
;                     *(u32x4*)(rowp + bj * HALF) = w; }
;                 if (isv) { sq += __shfl_xor(sq, 16); sq += __shfl_xor(sq, 32); if (fq == 0) unsafeAtomicAdd(ssv + grow, sq); } }
.LBB0_805:
	v_or_b32_e32 v150, 32, v148
	v_ashrrev_i32_e32 v151, 31, v150
	s_waitcnt lgkmcnt(0)
	v_lshl_add_u64 v[128:129], v[150:151], 2, s[66:67]
	v_mov_b32_e32 v128, v228
	s_mov_b32 s0, 0x20000
	v_fmamk_f32 v128, v128, 0x3a000000, v166
	v_rsq_f32_e32 v138, v128
	s_nop 0
	v_pk_mul_f32 v[130:131], v[108:109], v[138:139] op_sel_hi:[1,0]
	s_nop 0
	v_mul_f32_e32 v149, 0x3d922279, v130
	v_fmaak_f32 v149, v130, v149, 0x3fcc422a
	v_mul_f32_e32 v149, v130, v149
	v_mul_f32_e32 v149, 0xbfb8aa3b, v149
	v_exp_f32_e32 v149, v149
	v_pk_mul_f32 v[154:155], v[104:105], v[138:139] op_sel_hi:[1,0]
	v_pk_mul_f32 v[128:129], v[110:111], v[138:139] op_sel_hi:[1,0]
	v_pk_mul_f32 v[152:153], v[106:107], v[138:139] op_sel_hi:[1,0]
	v_add_f32_e32 v149, 1.0, v149
	v_rcp_f32_e32 v149, v149
	v_pk_mul_f32 v[156:157], v[76:77], v[138:139] op_sel_hi:[1,0]
	v_mul_f32_e32 v149, v130, v149
	v_mul_f32_e32 v130, 0x3d922279, v154
	v_fmaak_f32 v130, v154, v130, 0x3fcc422a
	v_mul_f32_e32 v130, v154, v130
	v_mul_f32_e32 v130, 0xbfb8aa3b, v130
	v_exp_f32_e32 v130, v130
	s_nop 0
	v_add_f32_e32 v130, 1.0, v130
	v_rcp_f32_e32 v130, v130
	s_nop 0
	v_mul_f32_e32 v167, v154, v130
	v_mul_f32_e32 v130, 0x3d922279, v131
	v_fmaak_f32 v130, v131, v130, 0x3fcc422a
	v_mul_f32_e32 v130, v131, v130
	v_mul_f32_e32 v130, 0xbfb8aa3b, v130
	v_exp_f32_e32 v130, v130
	s_nop 0
	v_add_f32_e32 v130, 1.0, v130
	v_rcp_f32_e32 v130, v130
	s_nop 0
	v_mul_f32_e32 v168, v131, v130
	v_mul_f32_e32 v130, 0x3d922279, v155
	v_fmaak_f32 v130, v155, v130, 0x3fcc422a
	v_mul_f32_e32 v130, v155, v130
	v_mul_f32_e32 v130, 0xbfb8aa3b, v130
	v_exp_f32_e32 v130, v130
	s_nop 0
	v_add_f32_e32 v130, 1.0, v130
	v_rcp_f32_e32 v130, v130
	s_nop 0
	v_mul_f32_e32 v169, v155, v130
	v_mul_f32_e32 v130, 0x3d922279, v128
	v_fmaak_f32 v130, v128, v130, 0x3fcc422a
	v_mul_f32_e32 v130, v128, v130
	v_mul_f32_e32 v130, 0xbfb8aa3b, v130
	v_exp_f32_e32 v130, v130
	v_pk_mul_f32 v[154:155], v[72:73], v[138:139] op_sel_hi:[1,0]
	v_add_f32_e32 v130, 1.0, v130
	v_rcp_f32_e32 v130, v130
	s_nop 0
	v_mul_f32_e32 v170, v128, v130
	v_mul_f32_e32 v128, 0x3d922279, v152
	v_fmaak_f32 v128, v152, v128, 0x3fcc422a
	v_mul_f32_e32 v128, v152, v128
	v_mul_f32_e32 v128, 0xbfb8aa3b, v128
	v_exp_f32_e32 v128, v128
	s_nop 0
	v_add_f32_e32 v128, 1.0, v128
	v_rcp_f32_e32 v128, v128
	s_nop 0
	v_mul_f32_e32 v171, v152, v128
	v_mul_f32_e32 v128, 0x3d922279, v129
	v_fmaak_f32 v128, v129, v128, 0x3fcc422a
	v_mul_f32_e32 v128, v129, v128
	v_mul_f32_e32 v128, 0xbfb8aa3b, v128
	v_exp_f32_e32 v128, v128
	v_add_co_u32_e32 v152, vcc, s0, v146
	v_add_f32_e32 v128, 1.0, v128
	v_rcp_f32_e32 v128, v128
	s_nop 0
	v_mul_f32_e32 v172, v129, v128
	v_mul_f32_e32 v128, 0x3d922279, v153
	v_fmaak_f32 v128, v153, v128, 0x3fcc422a
	v_mul_f32_e32 v128, v153, v128
	v_mul_f32_e32 v128, 0xbfb8aa3b, v128
	v_exp_f32_e32 v128, v128
	s_nop 0
	v_add_f32_e32 v128, 1.0, v128
	v_rcp_f32_e32 v128, v128
	s_nop 0
	v_mul_f32_e32 v173, v153, v128
	v_cvt_pk_bf16_f32 v128, v149, v168
	v_cvt_pk_bf16_f32 v129, v170, v172
	v_cvt_pk_bf16_f32 v130, v167, v169
	v_cvt_pk_bf16_f32 v131, v171, v173
	v_addc_co_u32_e32 v153, vcc, 0, v147, vcc
	global_store_dwordx4 v[152:153], v[128:131], off
	s_and_b64 vcc, exec, s[6:7]
	s_nop 0
	v_pk_mul_f32 v[130:131], v[78:79], v[138:139] op_sel_hi:[1,0]
	v_pk_mul_f32 v[128:129], v[74:75], v[138:139] op_sel_hi:[1,0]
	v_mul_f32_e32 v138, 0x3d922279, v156
	v_fmaak_f32 v138, v156, v138, 0x3fcc422a
	v_mul_f32_e32 v138, v156, v138
	v_mul_f32_e32 v138, 0xbfb8aa3b, v138
	v_exp_f32_e32 v138, v138
	s_nop 0
	v_add_f32_e32 v138, 1.0, v138
	v_rcp_f32_e32 v138, v138
	s_nop 0
	v_mul_f32_e32 v138, v156, v138
	v_mul_f32_e32 v156, 0x3d922279, v154
	v_fmaak_f32 v156, v154, v156, 0x3fcc422a
	v_mul_f32_e32 v156, v154, v156
	v_mul_f32_e32 v156, 0xbfb8aa3b, v156
	v_exp_f32_e32 v156, v156
	s_nop 0
	v_add_f32_e32 v156, 1.0, v156
	v_rcp_f32_e32 v156, v156
	s_nop 0
	v_mul_f32_e32 v154, v154, v156
	v_mul_f32_e32 v156, 0x3d922279, v157
	v_fmaak_f32 v156, v157, v156, 0x3fcc422a
	v_mul_f32_e32 v156, v157, v156
	v_mul_f32_e32 v156, 0xbfb8aa3b, v156
	v_exp_f32_e32 v156, v156
	s_nop 0
	v_add_f32_e32 v156, 1.0, v156
	v_rcp_f32_e32 v156, v156
	s_nop 0
	v_mul_f32_e32 v156, v157, v156
	v_mul_f32_e32 v157, 0x3d922279, v155
	v_fmaak_f32 v157, v155, v157, 0x3fcc422a
	v_mul_f32_e32 v157, v155, v157
	v_mul_f32_e32 v157, 0xbfb8aa3b, v157
	v_exp_f32_e32 v157, v157
	v_cvt_pk_bf16_f32 v174, v138, v156
	s_nop 0
	v_add_f32_e32 v157, 1.0, v157
	v_rcp_f32_e32 v157, v157
	s_nop 0
	v_mul_f32_e32 v155, v155, v157
	v_mul_f32_e32 v157, 0x3d922279, v130
	v_fmaak_f32 v157, v130, v157, 0x3fcc422a
	v_mul_f32_e32 v157, v130, v157
	v_mul_f32_e32 v157, 0xbfb8aa3b, v157
	v_exp_f32_e32 v157, v157
	s_nop 0
	v_add_f32_e32 v157, 1.0, v157
	v_rcp_f32_e32 v157, v157
	s_nop 0
	v_mul_f32_e32 v130, v130, v157
	v_mul_f32_e32 v157, 0x3d922279, v128
	v_fmaak_f32 v157, v128, v157, 0x3fcc422a
	v_mul_f32_e32 v157, v128, v157
	v_mul_f32_e32 v157, 0xbfb8aa3b, v157
	v_exp_f32_e32 v157, v157
	s_nop 0
	v_add_f32_e32 v157, 1.0, v157
	v_rcp_f32_e32 v157, v157
	s_nop 0
	v_mul_f32_e32 v128, v128, v157
	v_mul_f32_e32 v157, 0x3d922279, v131
	v_fmaak_f32 v157, v131, v157, 0x3fcc422a
	v_mul_f32_e32 v157, v131, v157
	v_mul_f32_e32 v157, 0xbfb8aa3b, v157
	v_exp_f32_e32 v157, v157
	s_nop 0
	v_add_f32_e32 v157, 1.0, v157
	v_rcp_f32_e32 v157, v157
	s_nop 0
	v_mul_f32_e32 v131, v131, v157
	v_mul_f32_e32 v157, 0x3d922279, v129
	v_fmaak_f32 v157, v129, v157, 0x3fcc422a
	v_mul_f32_e32 v157, v129, v157
	v_mul_f32_e32 v157, 0xbfb8aa3b, v157
	v_exp_f32_e32 v157, v157
	v_cvt_pk_bf16_f32 v175, v130, v131
	v_cvt_pk_bf16_f32 v176, v154, v155
	s_nop 0
	v_add_f32_e32 v157, 1.0, v157
	v_rcp_f32_e32 v157, v157
	s_nop 0
	v_mul_f32_e32 v129, v129, v157
	v_cvt_pk_bf16_f32 v177, v128, v129
	global_store_dwordx4 v[152:153], v[174:177], off offset:256
	s_cbranch_vccnz .LBB0_809
	v_mul_f32_e32 v153, v168, v168
	v_fmac_f32_e32 v153, v149, v149
	v_mul_f32_e32 v149, v172, v172
	v_mul_f32_e32 v129, v129, v129
	v_fmac_f32_e32 v149, v170, v170
	v_fmac_f32_e32 v129, v128, v128
	v_mul_f32_e32 v128, v156, v156
	v_mul_f32_e32 v131, v131, v131
	v_add_f32_e32 v149, v153, v149
	v_mul_f32_e32 v153, v169, v169
	v_fmac_f32_e32 v128, v138, v138
	v_fmac_f32_e32 v131, v130, v130
	v_mul_f32_e32 v130, v155, v155
	v_mul_f32_e32 v152, v173, v173
	v_fmac_f32_e32 v153, v167, v167
	v_add_f32_e32 v128, v128, v131
	v_fmac_f32_e32 v130, v154, v154
	v_fmac_f32_e32 v152, v171, v171
	v_add_f32_e32 v149, v153, v149
	v_add_f32_e32 v128, v130, v128
	v_add_f32_e32 v149, v152, v149
	v_add_f32_e32 v128, v129, v128
	v_add_f32_e32 v128, v149, v128
	ds_bpermute_b32 v129, v162, v128
	s_waitcnt lgkmcnt(0)
	v_add_f32_e32 v128, v128, v129
	ds_bpermute_b32 v129, v163, v128
	s_and_saveexec_b64 s[0:1], s[4:5]
	s_cbranch_execz .LBB0_808
	v_lshl_add_u64 v[130:131], v[150:151], 2, s[68:69]
	s_waitcnt lgkmcnt(0)
	v_add_f32_e32 v128, v128, v129
	global_atomic_add_f32 v[130:131], v128, off

; __device__ __forceinline__ unsigned cvt_pk_bf16(float lo, float hi) { unsigned r; asm volatile("v_cvt_pk_bf16_f32 %0, %1, %2" : "=v"(r) : "v"(lo), "v"(hi)); return r; }
; __device__ __forceinline__ float rstd_of(float ss) { return __builtin_amdgcn_rsqf(ss * (1.0f / 2048.0f) + NORM_EPS); }
; __device__ __forceinline__ float gelu_tanh(float x) { const float u = x * (1.5957691216057308f + 0.0713548162726009f * x * x); return x * sigmoid_f(u); }
;     __device__ __forceinline__ void operator()(const f32x4 (&acc)[2][2][4][2], const Unit& u, int wr, int wc, int fr, int fq) const {
;     ...
;             for (int m = 0; m < 4; ++m) { bf16_t* rowp = base + (size_t)(ai * HALF + m * 16) * LD; const int grow = u.pm * BM + ai * HALF + m * 16 + rt; const float rs = rstd_of(ssin[grow]); float sq = 0.f;
; #pragma unroll
;                 for (int bj = 0; bj < 2; ++bj) { f32x4 v0 = acc[ai][bj][m][0] * rs, v1 = acc[ai][bj][m][1] * rs;
; #pragma unroll
;                     for (int j = 0; j < 4; ++j) { v0[j] = gelu_tanh(v0[j]); v1[j] = gelu_tanh(v1[j]); }
;                     sq += (v0[0] * v0[0] + v0[1] * v0[1]) + (v0[2] * v0[2] + v0[3] * v0[3]) + (v1[0] * v1[0] + v1[1] * v1[1]) + (v1[2] * v1[2] + v1[3] * v1[3]);
;                     u32x4 w; w.x = cvt_pk_bf16(v0[0], v0[1]); w.y = cvt_pk_bf16(v0[2], v0[3]); w.z = cvt_pk_bf16(v1[0], v1[1]); w.w = cvt_pk_bf16(v1[2], v1[3]);
;                     *(u32x4*)(rowp + bj * HALF) = w; }
;                 if (isv) { sq += __shfl_xor(sq, 16); sq += __shfl_xor(sq, 32); if (fq == 0) unsafeAtomicAdd(ssv + grow, sq); } }
.LBB0_809:
	v_or_b32_e32 v150, 48, v148
	v_ashrrev_i32_e32 v151, 31, v150
	s_waitcnt lgkmcnt(0)
	v_lshl_add_u64 v[128:129], v[150:151], 2, s[66:67]
	v_mov_b32_e32 v128, v229
	s_mov_b32 s0, 0x30000
	v_fmamk_f32 v128, v128, 0x3a000000, v166
	v_rsq_f32_e32 v138, v128
	s_nop 0
	v_pk_mul_f32 v[130:131], v[100:101], v[138:139] op_sel_hi:[1,0]
	s_nop 0
	v_mul_f32_e32 v149, 0x3d922279, v130
	v_fmaak_f32 v149, v130, v149, 0x3fcc422a
	v_mul_f32_e32 v149, v130, v149
	v_mul_f32_e32 v149, 0xbfb8aa3b, v149
	v_exp_f32_e32 v149, v149
	v_pk_mul_f32 v[154:155], v[96:97], v[138:139] op_sel_hi:[1,0]
	v_pk_mul_f32 v[128:129], v[102:103], v[138:139] op_sel_hi:[1,0]
	v_pk_mul_f32 v[152:153], v[98:99], v[138:139] op_sel_hi:[1,0]
	v_add_f32_e32 v149, 1.0, v149
	v_rcp_f32_e32 v149, v149
	v_pk_mul_f32 v[156:157], v[68:69], v[138:139] op_sel_hi:[1,0]
	v_mul_f32_e32 v149, v130, v149
	v_mul_f32_e32 v130, 0x3d922279, v154
	v_fmaak_f32 v130, v154, v130, 0x3fcc422a
	v_mul_f32_e32 v130, v154, v130
	v_mul_f32_e32 v130, 0xbfb8aa3b, v130
	v_exp_f32_e32 v130, v130
	s_nop 0
	v_add_f32_e32 v130, 1.0, v130
	v_rcp_f32_e32 v130, v130
	s_nop 0
	v_mul_f32_e32 v167, v154, v130
	v_mul_f32_e32 v130, 0x3d922279, v131
	v_fmaak_f32 v130, v131, v130, 0x3fcc422a
	v_mul_f32_e32 v130, v131, v130
	v_mul_f32_e32 v130, 0xbfb8aa3b, v130
	v_exp_f32_e32 v130, v130
	s_nop 0
	v_add_f32_e32 v130, 1.0, v130
	v_rcp_f32_e32 v130, v130
	s_nop 0
	v_mul_f32_e32 v168, v131, v130
	v_mul_f32_e32 v130, 0x3d922279, v155
	v_fmaak_f32 v130, v155, v130, 0x3fcc422a
	v_mul_f32_e32 v130, v155, v130
	v_mul_f32_e32 v130, 0xbfb8aa3b, v130
	v_exp_f32_e32 v130, v130
	s_nop 0
	v_add_f32_e32 v130, 1.0, v130
	v_rcp_f32_e32 v130, v130
	s_nop 0
	v_mul_f32_e32 v169, v155, v130
	v_mul_f32_e32 v130, 0x3d922279, v128
	v_fmaak_f32 v130, v128, v130, 0x3fcc422a
	v_mul_f32_e32 v130, v128, v130
	v_mul_f32_e32 v130, 0xbfb8aa3b, v130
	v_exp_f32_e32 v130, v130
	v_pk_mul_f32 v[154:155], v[64:65], v[138:139] op_sel_hi:[1,0]
	v_add_f32_e32 v130, 1.0, v130
	v_rcp_f32_e32 v130, v130
	s_nop 0
	v_mul_f32_e32 v170, v128, v130
	v_mul_f32_e32 v128, 0x3d922279, v152
	v_fmaak_f32 v128, v152, v128, 0x3fcc422a
	v_mul_f32_e32 v128, v152, v128
	v_mul_f32_e32 v128, 0xbfb8aa3b, v128
	v_exp_f32_e32 v128, v128
	s_nop 0
	v_add_f32_e32 v128, 1.0, v128
	v_rcp_f32_e32 v128, v128
	s_nop 0
	v_mul_f32_e32 v171, v152, v128
	v_mul_f32_e32 v128, 0x3d922279, v129
	v_fmaak_f32 v128, v129, v128, 0x3fcc422a
	v_mul_f32_e32 v128, v129, v128
	v_mul_f32_e32 v128, 0xbfb8aa3b, v128
	v_exp_f32_e32 v128, v128
	v_add_co_u32_e32 v152, vcc, s0, v146
	v_add_f32_e32 v128, 1.0, v128
	v_rcp_f32_e32 v128, v128
	s_nop 0
	v_mul_f32_e32 v172, v129, v128
	v_mul_f32_e32 v128, 0x3d922279, v153
	v_fmaak_f32 v128, v153, v128, 0x3fcc422a
	v_mul_f32_e32 v128, v153, v128
	v_mul_f32_e32 v128, 0xbfb8aa3b, v128
	v_exp_f32_e32 v128, v128
	s_nop 0
	v_add_f32_e32 v128, 1.0, v128
	v_rcp_f32_e32 v128, v128
	s_nop 0
	v_mul_f32_e32 v173, v153, v128
	v_cvt_pk_bf16_f32 v128, v149, v168
	v_cvt_pk_bf16_f32 v129, v170, v172
	v_cvt_pk_bf16_f32 v130, v167, v169
	v_cvt_pk_bf16_f32 v131, v171, v173
	v_addc_co_u32_e32 v153, vcc, 0, v147, vcc
	global_store_dwordx4 v[152:153], v[128:131], off
	s_and_b64 vcc, exec, s[6:7]
	s_nop 0
	v_pk_mul_f32 v[130:131], v[70:71], v[138:139] op_sel_hi:[1,0]
	v_pk_mul_f32 v[128:129], v[66:67], v[138:139] op_sel_hi:[1,0]
	v_mul_f32_e32 v138, 0x3d922279, v156
	v_fmaak_f32 v138, v156, v138, 0x3fcc422a
	v_mul_f32_e32 v138, v156, v138
	v_mul_f32_e32 v138, 0xbfb8aa3b, v138
	v_exp_f32_e32 v138, v138
	s_nop 0
	v_add_f32_e32 v138, 1.0, v138
	v_rcp_f32_e32 v138, v138
	s_nop 0
	v_mul_f32_e32 v138, v156, v138
	v_mul_f32_e32 v156, 0x3d922279, v154
	v_fmaak_f32 v156, v154, v156, 0x3fcc422a
	v_mul_f32_e32 v156, v154, v156
	v_mul_f32_e32 v156, 0xbfb8aa3b, v156
	v_exp_f32_e32 v156, v156
	s_nop 0
	v_add_f32_e32 v156, 1.0, v156
	v_rcp_f32_e32 v156, v156
	s_nop 0
	v_mul_f32_e32 v154, v154, v156
	v_mul_f32_e32 v156, 0x3d922279, v157
	v_fmaak_f32 v156, v157, v156, 0x3fcc422a
	v_mul_f32_e32 v156, v157, v156
	v_mul_f32_e32 v156, 0xbfb8aa3b, v156
	v_exp_f32_e32 v156, v156
	s_nop 0
	v_add_f32_e32 v156, 1.0, v156
	v_rcp_f32_e32 v156, v156
	s_nop 0
	v_mul_f32_e32 v156, v157, v156
	v_mul_f32_e32 v157, 0x3d922279, v155
	v_fmaak_f32 v157, v155, v157, 0x3fcc422a
	v_mul_f32_e32 v157, v155, v157
	v_mul_f32_e32 v157, 0xbfb8aa3b, v157
	v_exp_f32_e32 v157, v157
	v_cvt_pk_bf16_f32 v174, v138, v156
	s_nop 0
	v_add_f32_e32 v157, 1.0, v157
	v_rcp_f32_e32 v157, v157
	s_nop 0
	v_mul_f32_e32 v155, v155, v157
	v_mul_f32_e32 v157, 0x3d922279, v130
	v_fmaak_f32 v157, v130, v157, 0x3fcc422a
	v_mul_f32_e32 v157, v130, v157
	v_mul_f32_e32 v157, 0xbfb8aa3b, v157
	v_exp_f32_e32 v157, v157
	s_nop 0
	v_add_f32_e32 v157, 1.0, v157
	v_rcp_f32_e32 v157, v157
	s_nop 0
	v_mul_f32_e32 v130, v130, v157
	v_mul_f32_e32 v157, 0x3d922279, v128
	v_fmaak_f32 v157, v128, v157, 0x3fcc422a
	v_mul_f32_e32 v157, v128, v157
	v_mul_f32_e32 v157, 0xbfb8aa3b, v157
	v_exp_f32_e32 v157, v157
	s_nop 0
	v_add_f32_e32 v157, 1.0, v157
	v_rcp_f32_e32 v157, v157
	s_nop 0
	v_mul_f32_e32 v128, v128, v157
	v_mul_f32_e32 v157, 0x3d922279, v131
	v_fmaak_f32 v157, v131, v157, 0x3fcc422a
	v_mul_f32_e32 v157, v131, v157
	v_mul_f32_e32 v157, 0xbfb8aa3b, v157
	v_exp_f32_e32 v157, v157
	s_nop 0
	v_add_f32_e32 v157, 1.0, v157
	v_rcp_f32_e32 v157, v157
	s_nop 0
	v_mul_f32_e32 v131, v131, v157
	v_mul_f32_e32 v157, 0x3d922279, v129
	v_fmaak_f32 v157, v129, v157, 0x3fcc422a
	v_mul_f32_e32 v157, v129, v157
	v_mul_f32_e32 v157, 0xbfb8aa3b, v157
	v_exp_f32_e32 v157, v157
	v_cvt_pk_bf16_f32 v175, v130, v131
	v_cvt_pk_bf16_f32 v176, v154, v155
	s_nop 0
	v_add_f32_e32 v157, 1.0, v157
	v_rcp_f32_e32 v157, v157
	s_nop 0
	v_mul_f32_e32 v129, v129, v157
	v_cvt_pk_bf16_f32 v177, v128, v129
	global_store_dwordx4 v[152:153], v[174:177], off offset:256
	s_cbranch_vccnz .LBB0_813
	v_mul_f32_e32 v153, v168, v168
	v_fmac_f32_e32 v153, v149, v149
	v_mul_f32_e32 v149, v172, v172
	v_mul_f32_e32 v129, v129, v129
	v_fmac_f32_e32 v149, v170, v170
	v_fmac_f32_e32 v129, v128, v128
	v_mul_f32_e32 v128, v156, v156
	v_mul_f32_e32 v131, v131, v131
	v_add_f32_e32 v149, v153, v149
	v_mul_f32_e32 v153, v169, v169
	v_fmac_f32_e32 v128, v138, v138
	v_fmac_f32_e32 v131, v130, v130
	v_mul_f32_e32 v130, v155, v155
	v_mul_f32_e32 v152, v173, v173
	v_fmac_f32_e32 v153, v167, v167
	v_add_f32_e32 v128, v128, v131
	v_fmac_f32_e32 v130, v154, v154
	v_fmac_f32_e32 v152, v171, v171
	v_add_f32_e32 v149, v153, v149
	v_add_f32_e32 v128, v130, v128
	v_add_f32_e32 v149, v152, v149
	v_add_f32_e32 v128, v129, v128
	v_add_f32_e32 v128, v149, v128
	ds_bpermute_b32 v129, v162, v128
	s_waitcnt lgkmcnt(0)
	v_add_f32_e32 v128, v128, v129
	ds_bpermute_b32 v129, v163, v128
	s_and_saveexec_b64 s[0:1], s[4:5]
	s_cbranch_execz .LBB0_812
	v_lshl_add_u64 v[130:131], v[150:151], 2, s[68:69]
	s_waitcnt lgkmcnt(0)
	v_add_f32_e32 v128, v128, v129
	global_atomic_add_f32 v[130:131], v128, off

; __device__ __forceinline__ unsigned cvt_pk_bf16(float lo, float hi) { unsigned r; asm volatile("v_cvt_pk_bf16_f32 %0, %1, %2" : "=v"(r) : "v"(lo), "v"(hi)); return r; }
; __device__ __forceinline__ float rstd_of(float ss) { return __builtin_amdgcn_rsqf(ss * (1.0f / 2048.0f) + NORM_EPS); }
; __device__ __forceinline__ float gelu_tanh(float x) { const float u = x * (1.5957691216057308f + 0.0713548162726009f * x * x); return x * sigmoid_f(u); }
;     __device__ __forceinline__ void operator()(const f32x4 (&acc)[2][2][4][2], const Unit& u, int wr, int wc, int fr, int fq) const {
;     ...
;             for (int m = 0; m < 4; ++m) { bf16_t* rowp = base + (size_t)(ai * HALF + m * 16) * LD; const int grow = u.pm * BM + ai * HALF + m * 16 + rt; const float rs = rstd_of(ssin[grow]); float sq = 0.f;
; #pragma unroll
;                 for (int bj = 0; bj < 2; ++bj) { f32x4 v0 = acc[ai][bj][m][0] * rs, v1 = acc[ai][bj][m][1] * rs;
; #pragma unroll
;                     for (int j = 0; j < 4; ++j) { v0[j] = gelu_tanh(v0[j]); v1[j] = gelu_tanh(v1[j]); }
;                     sq += (v0[0] * v0[0] + v0[1] * v0[1]) + (v0[2] * v0[2] + v0[3] * v0[3]) + (v1[0] * v1[0] + v1[1] * v1[1]) + (v1[2] * v1[2] + v1[3] * v1[3]);
;                     u32x4 w; w.x = cvt_pk_bf16(v0[0], v0[1]); w.y = cvt_pk_bf16(v0[2], v0[3]); w.z = cvt_pk_bf16(v1[0], v1[1]); w.w = cvt_pk_bf16(v1[2], v1[3]);
;                     *(u32x4*)(rowp + bj * HALF) = w; }
;                 if (isv) { sq += __shfl_xor(sq, 16); sq += __shfl_xor(sq, 32); if (fq == 0) unsafeAtomicAdd(ssv + grow, sq); } }
.LBB0_813:
	v_add_u32_e32 v148, 0x80, v148
	v_ashrrev_i32_e32 v149, 31, v148
	s_waitcnt lgkmcnt(0)
	v_lshl_add_u64 v[128:129], v[148:149], 2, s[66:67]
	v_mov_b32_e32 v128, v230
	s_mov_b32 s0, 0x80000
	v_fmamk_f32 v128, v128, 0x3a000000, v166
	v_rsq_f32_e32 v138, v128
	s_nop 0
	v_pk_mul_f32 v[130:131], v[60:61], v[138:139] op_sel_hi:[1,0]
	s_nop 0
	v_mul_f32_e32 v154, 0x3d922279, v130
	v_fmaak_f32 v154, v130, v154, 0x3fcc422a
	v_mul_f32_e32 v154, v130, v154
	v_mul_f32_e32 v154, 0xbfb8aa3b, v154
	v_exp_f32_e32 v154, v154
	v_pk_mul_f32 v[152:153], v[56:57], v[138:139] op_sel_hi:[1,0]
	v_pk_mul_f32 v[128:129], v[62:63], v[138:139] op_sel_hi:[1,0]
	v_pk_mul_f32 v[150:151], v[58:59], v[138:139] op_sel_hi:[1,0]
	v_add_f32_e32 v154, 1.0, v154
	v_rcp_f32_e32 v154, v154
	s_nop 0
	v_mul_f32_e32 v156, v130, v154
	v_mul_f32_e32 v130, 0x3d922279, v152
	v_fmaak_f32 v130, v152, v130, 0x3fcc422a
	v_mul_f32_e32 v130, v152, v130
	v_mul_f32_e32 v130, 0xbfb8aa3b, v130
	v_exp_f32_e32 v130, v130
	v_pk_mul_f32 v[154:155], v[28:29], v[138:139] op_sel_hi:[1,0]
	v_add_f32_e32 v130, 1.0, v130
	v_rcp_f32_e32 v130, v130
	s_nop 0
	v_mul_f32_e32 v157, v152, v130
	v_mul_f32_e32 v130, 0x3d922279, v131
	v_fmaak_f32 v130, v131, v130, 0x3fcc422a
	v_mul_f32_e32 v130, v131, v130
	v_mul_f32_e32 v130, 0xbfb8aa3b, v130
	v_exp_f32_e32 v130, v130
	s_nop 0
	v_add_f32_e32 v130, 1.0, v130
	v_rcp_f32_e32 v130, v130
	s_nop 0
	v_mul_f32_e32 v167, v131, v130
	v_mul_f32_e32 v130, 0x3d922279, v153
	v_fmaak_f32 v130, v153, v130, 0x3fcc422a
	v_mul_f32_e32 v130, v153, v130
	v_mul_f32_e32 v130, 0xbfb8aa3b, v130
	v_exp_f32_e32 v130, v130
	s_nop 0
	v_add_f32_e32 v130, 1.0, v130
	v_rcp_f32_e32 v130, v130
	s_nop 0
	v_mul_f32_e32 v168, v153, v130
	v_mul_f32_e32 v130, 0x3d922279, v128
	v_fmaak_f32 v130, v128, v130, 0x3fcc422a
	v_mul_f32_e32 v130, v128, v130
	v_mul_f32_e32 v130, 0xbfb8aa3b, v130
	v_exp_f32_e32 v130, v130
	v_pk_mul_f32 v[152:153], v[24:25], v[138:139] op_sel_hi:[1,0]
	v_add_f32_e32 v130, 1.0, v130
	v_rcp_f32_e32 v130, v130
	s_nop 0
	v_mul_f32_e32 v169, v128, v130
	v_mul_f32_e32 v128, 0x3d922279, v150
	v_fmaak_f32 v128, v150, v128, 0x3fcc422a
	v_mul_f32_e32 v128, v150, v128
	v_mul_f32_e32 v128, 0xbfb8aa3b, v128
	v_exp_f32_e32 v128, v128
	s_nop 0
	v_add_f32_e32 v128, 1.0, v128
	v_rcp_f32_e32 v128, v128
	s_nop 0
	v_mul_f32_e32 v170, v150, v128
	v_mul_f32_e32 v128, 0x3d922279, v129
	v_fmaak_f32 v128, v129, v128, 0x3fcc422a
	v_mul_f32_e32 v128, v129, v128
	v_mul_f32_e32 v128, 0xbfb8aa3b, v128
	v_exp_f32_e32 v128, v128
	v_add_co_u32_e32 v150, vcc, s0, v146
	v_add_f32_e32 v128, 1.0, v128
	v_rcp_f32_e32 v128, v128
	s_nop 0
	v_mul_f32_e32 v171, v129, v128
	v_mul_f32_e32 v128, 0x3d922279, v151
	v_fmaak_f32 v128, v151, v128, 0x3fcc422a
	v_mul_f32_e32 v128, v151, v128
	v_mul_f32_e32 v128, 0xbfb8aa3b, v128
	v_exp_f32_e32 v128, v128
	s_nop 0
	v_add_f32_e32 v128, 1.0, v128
	v_rcp_f32_e32 v128, v128
	s_nop 0
	v_mul_f32_e32 v172, v151, v128
	v_cvt_pk_bf16_f32 v128, v156, v167
	v_cvt_pk_bf16_f32 v129, v169, v171
	v_cvt_pk_bf16_f32 v130, v157, v168
	v_cvt_pk_bf16_f32 v131, v170, v172
	v_addc_co_u32_e32 v151, vcc, 0, v147, vcc
	global_store_dwordx4 v[150:151], v[128:131], off
	s_and_b64 vcc, exec, s[6:7]
	s_nop 0
	v_pk_mul_f32 v[130:131], v[30:31], v[138:139] op_sel_hi:[1,0]
	v_pk_mul_f32 v[128:129], v[26:27], v[138:139] op_sel_hi:[1,0]
	v_mul_f32_e32 v138, 0x3d922279, v154
	v_fmaak_f32 v138, v154, v138, 0x3fcc422a
	v_mul_f32_e32 v138, v154, v138
	v_mul_f32_e32 v138, 0xbfb8aa3b, v138
	v_exp_f32_e32 v138, v138
	s_nop 0
	v_add_f32_e32 v138, 1.0, v138
	v_rcp_f32_e32 v138, v138
	s_nop 0
	v_mul_f32_e32 v138, v154, v138
	v_mul_f32_e32 v154, 0x3d922279, v152
	v_fmaak_f32 v154, v152, v154, 0x3fcc422a
	v_mul_f32_e32 v154, v152, v154
	v_mul_f32_e32 v154, 0xbfb8aa3b, v154
	v_exp_f32_e32 v154, v154
	s_nop 0
	v_add_f32_e32 v154, 1.0, v154
	v_rcp_f32_e32 v154, v154
	s_nop 0
	v_mul_f32_e32 v152, v152, v154
	v_mul_f32_e32 v154, 0x3d922279, v155
	v_fmaak_f32 v154, v155, v154, 0x3fcc422a
	v_mul_f32_e32 v154, v155, v154
	v_mul_f32_e32 v154, 0xbfb8aa3b, v154
	v_exp_f32_e32 v154, v154
	s_nop 0
	v_add_f32_e32 v154, 1.0, v154
	v_rcp_f32_e32 v154, v154
	s_nop 0
	v_mul_f32_e32 v154, v155, v154
	v_mul_f32_e32 v155, 0x3d922279, v153
	v_fmaak_f32 v155, v153, v155, 0x3fcc422a
	v_mul_f32_e32 v155, v153, v155
	v_mul_f32_e32 v155, 0xbfb8aa3b, v155
	v_exp_f32_e32 v155, v155
	v_cvt_pk_bf16_f32 v174, v138, v154
	s_nop 0
	v_add_f32_e32 v155, 1.0, v155
	v_rcp_f32_e32 v155, v155
	s_nop 0
	v_mul_f32_e32 v153, v153, v155
	v_mul_f32_e32 v155, 0x3d922279, v130
	v_fmaak_f32 v155, v130, v155, 0x3fcc422a
	v_mul_f32_e32 v155, v130, v155
	v_mul_f32_e32 v155, 0xbfb8aa3b, v155
	v_exp_f32_e32 v155, v155
	s_nop 0
	v_add_f32_e32 v155, 1.0, v155
	v_rcp_f32_e32 v155, v155
	s_nop 0
	v_mul_f32_e32 v130, v130, v155
	v_mul_f32_e32 v155, 0x3d922279, v128
	v_fmaak_f32 v155, v128, v155, 0x3fcc422a
	v_mul_f32_e32 v155, v128, v155
	v_mul_f32_e32 v155, 0xbfb8aa3b, v155
	v_exp_f32_e32 v155, v155
	s_nop 0
	v_add_f32_e32 v155, 1.0, v155
	v_rcp_f32_e32 v155, v155
	s_nop 0
	v_mul_f32_e32 v128, v128, v155
	v_mul_f32_e32 v155, 0x3d922279, v131
	v_fmaak_f32 v155, v131, v155, 0x3fcc422a
	v_mul_f32_e32 v155, v131, v155
	v_mul_f32_e32 v155, 0xbfb8aa3b, v155
	v_exp_f32_e32 v155, v155
	s_nop 0
	v_add_f32_e32 v155, 1.0, v155
	v_rcp_f32_e32 v155, v155
	s_nop 0
	v_mul_f32_e32 v131, v131, v155
	v_mul_f32_e32 v155, 0x3d922279, v129
	v_fmaak_f32 v155, v129, v155, 0x3fcc422a
	v_mul_f32_e32 v155, v129, v155
	v_mul_f32_e32 v155, 0xbfb8aa3b, v155
	v_exp_f32_e32 v155, v155
	v_cvt_pk_bf16_f32 v175, v130, v131
	v_cvt_pk_bf16_f32 v176, v152, v153
	s_nop 0
	v_add_f32_e32 v155, 1.0, v155
	v_rcp_f32_e32 v155, v155
	s_nop 0
	v_mul_f32_e32 v129, v129, v155
	v_cvt_pk_bf16_f32 v177, v128, v129
	global_store_dwordx4 v[150:151], v[174:177], off offset:256
	s_cbranch_vccnz .LBB0_817
	v_mul_f32_e32 v151, v167, v167
	v_mul_f32_e32 v155, v171, v171
	v_mul_f32_e32 v129, v129, v129
	v_fmac_f32_e32 v151, v156, v156
	v_fmac_f32_e32 v155, v169, v169
	v_fmac_f32_e32 v129, v128, v128
	v_mul_f32_e32 v128, v154, v154
	v_mul_f32_e32 v131, v131, v131
	v_add_f32_e32 v151, v151, v155
	v_mul_f32_e32 v155, v168, v168
	v_fmac_f32_e32 v128, v138, v138
	v_fmac_f32_e32 v131, v130, v130
	v_mul_f32_e32 v130, v153, v153
	v_mul_f32_e32 v150, v172, v172
	v_fmac_f32_e32 v155, v157, v157
	v_add_f32_e32 v128, v128, v131
	v_fmac_f32_e32 v130, v152, v152
	v_fmac_f32_e32 v150, v170, v170
	v_add_f32_e32 v151, v155, v151
	v_add_f32_e32 v128, v130, v128
	v_add_f32_e32 v150, v150, v151
	v_add_f32_e32 v128, v129, v128
	v_add_f32_e32 v128, v150, v128
	ds_bpermute_b32 v129, v162, v128
	s_waitcnt lgkmcnt(0)
	v_add_f32_e32 v128, v128, v129
	ds_bpermute_b32 v129, v163, v128
	s_and_saveexec_b64 s[0:1], s[4:5]
	s_cbranch_execz .LBB0_816
	v_lshl_add_u64 v[130:131], v[148:149], 2, s[68:69]
	s_waitcnt lgkmcnt(0)
	v_add_f32_e32 v128, v128, v129
	global_atomic_add_f32 v[130:131], v128, off

; __device__ __forceinline__ unsigned cvt_pk_bf16(float lo, float hi) { unsigned r; asm volatile("v_cvt_pk_bf16_f32 %0, %1, %2" : "=v"(r) : "v"(lo), "v"(hi)); return r; }
; __device__ __forceinline__ float rstd_of(float ss) { return __builtin_amdgcn_rsqf(ss * (1.0f / 2048.0f) + NORM_EPS); }
; __device__ __forceinline__ float gelu_tanh(float x) { const float u = x * (1.5957691216057308f + 0.0713548162726009f * x * x); return x * sigmoid_f(u); }
;     __device__ __forceinline__ void operator()(const f32x4 (&acc)[2][2][4][2], const Unit& u, int wr, int wc, int fr, int fq) const {
;     ...
;             for (int m = 0; m < 4; ++m) { bf16_t* rowp = base + (size_t)(ai * HALF + m * 16) * LD; const int grow = u.pm * BM + ai * HALF + m * 16 + rt; const float rs = rstd_of(ssin[grow]); float sq = 0.f;
; #pragma unroll
;                 for (int bj = 0; bj < 2; ++bj) { f32x4 v0 = acc[ai][bj][m][0] * rs, v1 = acc[ai][bj][m][1] * rs;
; #pragma unroll
;                     for (int j = 0; j < 4; ++j) { v0[j] = gelu_tanh(v0[j]); v1[j] = gelu_tanh(v1[j]); }
;                     sq += (v0[0] * v0[0] + v0[1] * v0[1]) + (v0[2] * v0[2] + v0[3] * v0[3]) + (v1[0] * v1[0] + v1[1] * v1[1]) + (v1[2] * v1[2] + v1[3] * v1[3]);
;                     u32x4 w; w.x = cvt_pk_bf16(v0[0], v0[1]); w.y = cvt_pk_bf16(v0[2], v0[3]); w.z = cvt_pk_bf16(v1[0], v1[1]); w.w = cvt_pk_bf16(v1[2], v1[3]);
;                     *(u32x4*)(rowp + bj * HALF) = w; }
;                 if (isv) { sq += __shfl_xor(sq, 16); sq += __shfl_xor(sq, 32); if (fq == 0) unsafeAtomicAdd(ssv + grow, sq); } }
.LBB0_817:
	v_or_b32_e32 v150, 16, v148
	v_ashrrev_i32_e32 v151, 31, v150
	s_waitcnt lgkmcnt(0)
	v_lshl_add_u64 v[128:129], v[150:151], 2, s[66:67]
	v_mov_b32_e32 v128, v231
	s_mov_b32 s0, 0x90000
	v_fmamk_f32 v128, v128, 0x3a000000, v166
	v_rsq_f32_e32 v138, v128
	s_nop 0
	v_pk_mul_f32 v[130:131], v[52:53], v[138:139] op_sel_hi:[1,0]
	s_nop 0
	v_mul_f32_e32 v149, 0x3d922279, v130
	v_fmaak_f32 v149, v130, v149, 0x3fcc422a
	v_mul_f32_e32 v149, v130, v149
	v_mul_f32_e32 v149, 0xbfb8aa3b, v149
	v_exp_f32_e32 v149, v149
	v_pk_mul_f32 v[154:155], v[48:49], v[138:139] op_sel_hi:[1,0]
	v_pk_mul_f32 v[128:129], v[54:55], v[138:139] op_sel_hi:[1,0]
	v_pk_mul_f32 v[152:153], v[50:51], v[138:139] op_sel_hi:[1,0]
	v_add_f32_e32 v149, 1.0, v149
	v_rcp_f32_e32 v149, v149
	v_pk_mul_f32 v[156:157], v[20:21], v[138:139] op_sel_hi:[1,0]
	v_mul_f32_e32 v149, v130, v149
	v_mul_f32_e32 v130, 0x3d922279, v154
	v_fmaak_f32 v130, v154, v130, 0x3fcc422a
	v_mul_f32_e32 v130, v154, v130
	v_mul_f32_e32 v130, 0xbfb8aa3b, v130
	v_exp_f32_e32 v130, v130
	s_nop 0
	v_add_f32_e32 v130, 1.0, v130
	v_rcp_f32_e32 v130, v130
	s_nop 0
	v_mul_f32_e32 v167, v154, v130
	v_mul_f32_e32 v130, 0x3d922279, v131
	v_fmaak_f32 v130, v131, v130, 0x3fcc422a
	v_mul_f32_e32 v130, v131, v130
	v_mul_f32_e32 v130, 0xbfb8aa3b, v130
	v_exp_f32_e32 v130, v130
	s_nop 0
	v_add_f32_e32 v130, 1.0, v130
	v_rcp_f32_e32 v130, v130
	s_nop 0
	v_mul_f32_e32 v168, v131, v130
	v_mul_f32_e32 v130, 0x3d922279, v155
	v_fmaak_f32 v130, v155, v130, 0x3fcc422a
	v_mul_f32_e32 v130, v155, v130
	v_mul_f32_e32 v130, 0xbfb8aa3b, v130
	v_exp_f32_e32 v130, v130
	s_nop 0
	v_add_f32_e32 v130, 1.0, v130
	v_rcp_f32_e32 v130, v130
	s_nop 0
	v_mul_f32_e32 v169, v155, v130
	v_mul_f32_e32 v130, 0x3d922279, v128
	v_fmaak_f32 v130, v128, v130, 0x3fcc422a
	v_mul_f32_e32 v130, v128, v130
	v_mul_f32_e32 v130, 0xbfb8aa3b, v130
	v_exp_f32_e32 v130, v130
	v_pk_mul_f32 v[154:155], v[16:17], v[138:139] op_sel_hi:[1,0]
	v_add_f32_e32 v130, 1.0, v130
	v_rcp_f32_e32 v130, v130
	s_nop 0
	v_mul_f32_e32 v170, v128, v130
	v_mul_f32_e32 v128, 0x3d922279, v152
	v_fmaak_f32 v128, v152, v128, 0x3fcc422a
	v_mul_f32_e32 v128, v152, v128
	v_mul_f32_e32 v128, 0xbfb8aa3b, v128
	v_exp_f32_e32 v128, v128
	s_nop 0
	v_add_f32_e32 v128, 1.0, v128
	v_rcp_f32_e32 v128, v128
	s_nop 0
	v_mul_f32_e32 v171, v152, v128
	v_mul_f32_e32 v128, 0x3d922279, v129
	v_fmaak_f32 v128, v129, v128, 0x3fcc422a
	v_mul_f32_e32 v128, v129, v128
	v_mul_f32_e32 v128, 0xbfb8aa3b, v128
	v_exp_f32_e32 v128, v128
	v_add_co_u32_e32 v152, vcc, s0, v146
	v_add_f32_e32 v128, 1.0, v128
	v_rcp_f32_e32 v128, v128
	s_nop 0
	v_mul_f32_e32 v172, v129, v128
	v_mul_f32_e32 v128, 0x3d922279, v153
	v_fmaak_f32 v128, v153, v128, 0x3fcc422a
	v_mul_f32_e32 v128, v153, v128
	v_mul_f32_e32 v128, 0xbfb8aa3b, v128
	v_exp_f32_e32 v128, v128
	s_nop 0
	v_add_f32_e32 v128, 1.0, v128
	v_rcp_f32_e32 v128, v128
	s_nop 0
	v_mul_f32_e32 v173, v153, v128
	v_cvt_pk_bf16_f32 v128, v149, v168
	v_cvt_pk_bf16_f32 v129, v170, v172
	v_cvt_pk_bf16_f32 v130, v167, v169
	v_cvt_pk_bf16_f32 v131, v171, v173
	v_addc_co_u32_e32 v153, vcc, 0, v147, vcc
	global_store_dwordx4 v[152:153], v[128:131], off
	s_and_b64 vcc, exec, s[6:7]
	s_nop 0
	v_pk_mul_f32 v[130:131], v[22:23], v[138:139] op_sel_hi:[1,0]
	v_pk_mul_f32 v[128:129], v[18:19], v[138:139] op_sel_hi:[1,0]
	v_mul_f32_e32 v138, 0x3d922279, v156
	v_fmaak_f32 v138, v156, v138, 0x3fcc422a
	v_mul_f32_e32 v138, v156, v138
	v_mul_f32_e32 v138, 0xbfb8aa3b, v138
	v_exp_f32_e32 v138, v138
	s_nop 0
	v_add_f32_e32 v138, 1.0, v138
	v_rcp_f32_e32 v138, v138
	s_nop 0
	v_mul_f32_e32 v138, v156, v138
	v_mul_f32_e32 v156, 0x3d922279, v154
	v_fmaak_f32 v156, v154, v156, 0x3fcc422a
	v_mul_f32_e32 v156, v154, v156
	v_mul_f32_e32 v156, 0xbfb8aa3b, v156
	v_exp_f32_e32 v156, v156
	s_nop 0
	v_add_f32_e32 v156, 1.0, v156
	v_rcp_f32_e32 v156, v156
	s_nop 0
	v_mul_f32_e32 v154, v154, v156
	v_mul_f32_e32 v156, 0x3d922279, v157
	v_fmaak_f32 v156, v157, v156, 0x3fcc422a
	v_mul_f32_e32 v156, v157, v156
	v_mul_f32_e32 v156, 0xbfb8aa3b, v156
	v_exp_f32_e32 v156, v156
	s_nop 0
	v_add_f32_e32 v156, 1.0, v156
	v_rcp_f32_e32 v156, v156
	s_nop 0
	v_mul_f32_e32 v156, v157, v156
	v_mul_f32_e32 v157, 0x3d922279, v155
	v_fmaak_f32 v157, v155, v157, 0x3fcc422a
	v_mul_f32_e32 v157, v155, v157
	v_mul_f32_e32 v157, 0xbfb8aa3b, v157
	v_exp_f32_e32 v157, v157
	v_cvt_pk_bf16_f32 v174, v138, v156
	s_nop 0
	v_add_f32_e32 v157, 1.0, v157
	v_rcp_f32_e32 v157, v157
	s_nop 0
	v_mul_f32_e32 v155, v155, v157
	v_mul_f32_e32 v157, 0x3d922279, v130
	v_fmaak_f32 v157, v130, v157, 0x3fcc422a
	v_mul_f32_e32 v157, v130, v157
	v_mul_f32_e32 v157, 0xbfb8aa3b, v157
	v_exp_f32_e32 v157, v157
	s_nop 0
	v_add_f32_e32 v157, 1.0, v157
	v_rcp_f32_e32 v157, v157
	s_nop 0
	v_mul_f32_e32 v130, v130, v157
	v_mul_f32_e32 v157, 0x3d922279, v128
	v_fmaak_f32 v157, v128, v157, 0x3fcc422a
	v_mul_f32_e32 v157, v128, v157
	v_mul_f32_e32 v157, 0xbfb8aa3b, v157
	v_exp_f32_e32 v157, v157
	s_nop 0
	v_add_f32_e32 v157, 1.0, v157
	v_rcp_f32_e32 v157, v157
	s_nop 0
	v_mul_f32_e32 v128, v128, v157
	v_mul_f32_e32 v157, 0x3d922279, v131
	v_fmaak_f32 v157, v131, v157, 0x3fcc422a
	v_mul_f32_e32 v157, v131, v157
	v_mul_f32_e32 v157, 0xbfb8aa3b, v157
	v_exp_f32_e32 v157, v157
	s_nop 0
	v_add_f32_e32 v157, 1.0, v157
	v_rcp_f32_e32 v157, v157
	s_nop 0
	v_mul_f32_e32 v131, v131, v157
	v_mul_f32_e32 v157, 0x3d922279, v129
	v_fmaak_f32 v157, v129, v157, 0x3fcc422a
	v_mul_f32_e32 v157, v129, v157
	v_mul_f32_e32 v157, 0xbfb8aa3b, v157
	v_exp_f32_e32 v157, v157
	v_cvt_pk_bf16_f32 v175, v130, v131
	v_cvt_pk_bf16_f32 v176, v154, v155
	s_nop 0
	v_add_f32_e32 v157, 1.0, v157
	v_rcp_f32_e32 v157, v157
	s_nop 0
	v_mul_f32_e32 v129, v129, v157
	v_cvt_pk_bf16_f32 v177, v128, v129
	global_store_dwordx4 v[152:153], v[174:177], off offset:256
	s_cbranch_vccnz .LBB0_821
	v_mul_f32_e32 v153, v168, v168
	v_fmac_f32_e32 v153, v149, v149
	v_mul_f32_e32 v149, v172, v172
	v_mul_f32_e32 v129, v129, v129
	v_fmac_f32_e32 v149, v170, v170
	v_fmac_f32_e32 v129, v128, v128
	v_mul_f32_e32 v128, v156, v156
	v_mul_f32_e32 v131, v131, v131
	v_add_f32_e32 v149, v153, v149
	v_mul_f32_e32 v153, v169, v169
	v_fmac_f32_e32 v128, v138, v138
	v_fmac_f32_e32 v131, v130, v130
	v_mul_f32_e32 v130, v155, v155
	v_mul_f32_e32 v152, v173, v173
	v_fmac_f32_e32 v153, v167, v167
	v_add_f32_e32 v128, v128, v131
	v_fmac_f32_e32 v130, v154, v154
	v_fmac_f32_e32 v152, v171, v171
	v_add_f32_e32 v149, v153, v149
	v_add_f32_e32 v128, v130, v128
	v_add_f32_e32 v149, v152, v149
	v_add_f32_e32 v128, v129, v128
	v_add_f32_e32 v128, v149, v128
	ds_bpermute_b32 v129, v162, v128
	s_waitcnt lgkmcnt(0)
	v_add_f32_e32 v128, v128, v129
	ds_bpermute_b32 v129, v163, v128
	s_and_saveexec_b64 s[0:1], s[4:5]
	s_cbranch_execz .LBB0_820
	v_lshl_add_u64 v[130:131], v[150:151], 2, s[68:69]
	s_waitcnt lgkmcnt(0)
	v_add_f32_e32 v128, v128, v129
	global_atomic_add_f32 v[130:131], v128, off

; __device__ __forceinline__ unsigned cvt_pk_bf16(float lo, float hi) { unsigned r; asm volatile("v_cvt_pk_bf16_f32 %0, %1, %2" : "=v"(r) : "v"(lo), "v"(hi)); return r; }
; __device__ __forceinline__ float rstd_of(float ss) { return __builtin_amdgcn_rsqf(ss * (1.0f / 2048.0f) + NORM_EPS); }
; __device__ __forceinline__ float gelu_tanh(float x) { const float u = x * (1.5957691216057308f + 0.0713548162726009f * x * x); return x * sigmoid_f(u); }
;     __device__ __forceinline__ void operator()(const f32x4 (&acc)[2][2][4][2], const Unit& u, int wr, int wc, int fr, int fq) const {
;     ...
;             for (int m = 0; m < 4; ++m) { bf16_t* rowp = base + (size_t)(ai * HALF + m * 16) * LD; const int grow = u.pm * BM + ai * HALF + m * 16 + rt; const float rs = rstd_of(ssin[grow]); float sq = 0.f;
; #pragma unroll
;                 for (int bj = 0; bj < 2; ++bj) { f32x4 v0 = acc[ai][bj][m][0] * rs, v1 = acc[ai][bj][m][1] * rs;
; #pragma unroll
;                     for (int j = 0; j < 4; ++j) { v0[j] = gelu_tanh(v0[j]); v1[j] = gelu_tanh(v1[j]); }
;                     sq += (v0[0] * v0[0] + v0[1] * v0[1]) + (v0[2] * v0[2] + v0[3] * v0[3]) + (v1[0] * v1[0] + v1[1] * v1[1]) + (v1[2] * v1[2] + v1[3] * v1[3]);
;                     u32x4 w; w.x = cvt_pk_bf16(v0[0], v0[1]); w.y = cvt_pk_bf16(v0[2], v0[3]); w.z = cvt_pk_bf16(v1[0], v1[1]); w.w = cvt_pk_bf16(v1[2], v1[3]);
;                     *(u32x4*)(rowp + bj * HALF) = w; }
;                 if (isv) { sq += __shfl_xor(sq, 16); sq += __shfl_xor(sq, 32); if (fq == 0) unsafeAtomicAdd(ssv + grow, sq); } }
.LBB0_821:
	v_or_b32_e32 v150, 32, v148
	v_ashrrev_i32_e32 v151, 31, v150
	s_waitcnt lgkmcnt(0)
	v_lshl_add_u64 v[128:129], v[150:151], 2, s[66:67]
	v_mov_b32_e32 v128, v232
	s_mov_b32 s0, 0xa0000
	v_fmamk_f32 v128, v128, 0x3a000000, v166
	v_rsq_f32_e32 v138, v128
	s_nop 0
	v_pk_mul_f32 v[130:131], v[44:45], v[138:139] op_sel_hi:[1,0]
	s_nop 0
	v_mul_f32_e32 v149, 0x3d922279, v130
	v_fmaak_f32 v149, v130, v149, 0x3fcc422a
	v_mul_f32_e32 v149, v130, v149
	v_mul_f32_e32 v149, 0xbfb8aa3b, v149
	v_exp_f32_e32 v149, v149
	v_pk_mul_f32 v[154:155], v[40:41], v[138:139] op_sel_hi:[1,0]
	v_pk_mul_f32 v[128:129], v[46:47], v[138:139] op_sel_hi:[1,0]
	v_pk_mul_f32 v[152:153], v[42:43], v[138:139] op_sel_hi:[1,0]
	v_add_f32_e32 v149, 1.0, v149
	v_rcp_f32_e32 v149, v149
	v_pk_mul_f32 v[156:157], v[12:13], v[138:139] op_sel_hi:[1,0]
	v_mul_f32_e32 v149, v130, v149
	v_mul_f32_e32 v130, 0x3d922279, v154
	v_fmaak_f32 v130, v154, v130, 0x3fcc422a
	v_mul_f32_e32 v130, v154, v130
	v_mul_f32_e32 v130, 0xbfb8aa3b, v130
	v_exp_f32_e32 v130, v130
	s_nop 0
	v_add_f32_e32 v130, 1.0, v130
	v_rcp_f32_e32 v130, v130
	s_nop 0
	v_mul_f32_e32 v167, v154, v130
	v_mul_f32_e32 v130, 0x3d922279, v131
	v_fmaak_f32 v130, v131, v130, 0x3fcc422a
	v_mul_f32_e32 v130, v131, v130
	v_mul_f32_e32 v130, 0xbfb8aa3b, v130
	v_exp_f32_e32 v130, v130
	s_nop 0
	v_add_f32_e32 v130, 1.0, v130
	v_rcp_f32_e32 v130, v130
	s_nop 0
	v_mul_f32_e32 v168, v131, v130
	v_mul_f32_e32 v130, 0x3d922279, v155
	v_fmaak_f32 v130, v155, v130, 0x3fcc422a
	v_mul_f32_e32 v130, v155, v130
	v_mul_f32_e32 v130, 0xbfb8aa3b, v130
	v_exp_f32_e32 v130, v130
	s_nop 0
	v_add_f32_e32 v130, 1.0, v130
	v_rcp_f32_e32 v130, v130
	s_nop 0
	v_mul_f32_e32 v169, v155, v130
	v_mul_f32_e32 v130, 0x3d922279, v128
	v_fmaak_f32 v130, v128, v130, 0x3fcc422a
	v_mul_f32_e32 v130, v128, v130
	v_mul_f32_e32 v130, 0xbfb8aa3b, v130
	v_exp_f32_e32 v130, v130
	v_pk_mul_f32 v[154:155], v[8:9], v[138:139] op_sel_hi:[1,0]
	v_add_f32_e32 v130, 1.0, v130
	v_rcp_f32_e32 v130, v130
	s_nop 0
	v_mul_f32_e32 v170, v128, v130
	v_mul_f32_e32 v128, 0x3d922279, v152
	v_fmaak_f32 v128, v152, v128, 0x3fcc422a
	v_mul_f32_e32 v128, v152, v128
	v_mul_f32_e32 v128, 0xbfb8aa3b, v128
	v_exp_f32_e32 v128, v128
	s_nop 0
	v_add_f32_e32 v128, 1.0, v128
	v_rcp_f32_e32 v128, v128
	s_nop 0
	v_mul_f32_e32 v171, v152, v128
	v_mul_f32_e32 v128, 0x3d922279, v129
	v_fmaak_f32 v128, v129, v128, 0x3fcc422a
	v_mul_f32_e32 v128, v129, v128
	v_mul_f32_e32 v128, 0xbfb8aa3b, v128
	v_exp_f32_e32 v128, v128
	v_add_co_u32_e32 v152, vcc, s0, v146
	v_add_f32_e32 v128, 1.0, v128
	v_rcp_f32_e32 v128, v128
	s_nop 0
	v_mul_f32_e32 v172, v129, v128
	v_mul_f32_e32 v128, 0x3d922279, v153
	v_fmaak_f32 v128, v153, v128, 0x3fcc422a
	v_mul_f32_e32 v128, v153, v128
	v_mul_f32_e32 v128, 0xbfb8aa3b, v128
	v_exp_f32_e32 v128, v128
	s_nop 0
	v_add_f32_e32 v128, 1.0, v128
	v_rcp_f32_e32 v128, v128
	s_nop 0
	v_mul_f32_e32 v173, v153, v128
	v_cvt_pk_bf16_f32 v128, v149, v168
	v_cvt_pk_bf16_f32 v129, v170, v172
	v_cvt_pk_bf16_f32 v130, v167, v169
	v_cvt_pk_bf16_f32 v131, v171, v173
	v_addc_co_u32_e32 v153, vcc, 0, v147, vcc
	global_store_dwordx4 v[152:153], v[128:131], off
	s_and_b64 vcc, exec, s[6:7]
	s_nop 0
	v_pk_mul_f32 v[130:131], v[14:15], v[138:139] op_sel_hi:[1,0]
	v_pk_mul_f32 v[128:129], v[10:11], v[138:139] op_sel_hi:[1,0]
	v_mul_f32_e32 v138, 0x3d922279, v156
	v_fmaak_f32 v138, v156, v138, 0x3fcc422a
	v_mul_f32_e32 v138, v156, v138
	v_mul_f32_e32 v138, 0xbfb8aa3b, v138
	v_exp_f32_e32 v138, v138
	s_nop 0
	v_add_f32_e32 v138, 1.0, v138
	v_rcp_f32_e32 v138, v138
	s_nop 0
	v_mul_f32_e32 v138, v156, v138
	v_mul_f32_e32 v156, 0x3d922279, v154
	v_fmaak_f32 v156, v154, v156, 0x3fcc422a
	v_mul_f32_e32 v156, v154, v156
	v_mul_f32_e32 v156, 0xbfb8aa3b, v156
	v_exp_f32_e32 v156, v156
	s_nop 0
	v_add_f32_e32 v156, 1.0, v156
	v_rcp_f32_e32 v156, v156
	s_nop 0
	v_mul_f32_e32 v154, v154, v156
	v_mul_f32_e32 v156, 0x3d922279, v157
	v_fmaak_f32 v156, v157, v156, 0x3fcc422a
	v_mul_f32_e32 v156, v157, v156
	v_mul_f32_e32 v156, 0xbfb8aa3b, v156
	v_exp_f32_e32 v156, v156
	s_nop 0
	v_add_f32_e32 v156, 1.0, v156
	v_rcp_f32_e32 v156, v156
	s_nop 0
	v_mul_f32_e32 v156, v157, v156
	v_mul_f32_e32 v157, 0x3d922279, v155
	v_fmaak_f32 v157, v155, v157, 0x3fcc422a
	v_mul_f32_e32 v157, v155, v157
	v_mul_f32_e32 v157, 0xbfb8aa3b, v157
	v_exp_f32_e32 v157, v157
	v_cvt_pk_bf16_f32 v174, v138, v156
	s_nop 0
	v_add_f32_e32 v157, 1.0, v157
	v_rcp_f32_e32 v157, v157
	s_nop 0
	v_mul_f32_e32 v155, v155, v157
	v_mul_f32_e32 v157, 0x3d922279, v130
	v_fmaak_f32 v157, v130, v157, 0x3fcc422a
	v_mul_f32_e32 v157, v130, v157
	v_mul_f32_e32 v157, 0xbfb8aa3b, v157
	v_exp_f32_e32 v157, v157
	s_nop 0
	v_add_f32_e32 v157, 1.0, v157
	v_rcp_f32_e32 v157, v157
	s_nop 0
	v_mul_f32_e32 v130, v130, v157
	v_mul_f32_e32 v157, 0x3d922279, v128
	v_fmaak_f32 v157, v128, v157, 0x3fcc422a
	v_mul_f32_e32 v157, v128, v157
	v_mul_f32_e32 v157, 0xbfb8aa3b, v157
	v_exp_f32_e32 v157, v157
	s_nop 0
	v_add_f32_e32 v157, 1.0, v157
	v_rcp_f32_e32 v157, v157
	s_nop 0
	v_mul_f32_e32 v128, v128, v157
	v_mul_f32_e32 v157, 0x3d922279, v131
	v_fmaak_f32 v157, v131, v157, 0x3fcc422a
	v_mul_f32_e32 v157, v131, v157
	v_mul_f32_e32 v157, 0xbfb8aa3b, v157
	v_exp_f32_e32 v157, v157
	s_nop 0
	v_add_f32_e32 v157, 1.0, v157
	v_rcp_f32_e32 v157, v157
	s_nop 0
	v_mul_f32_e32 v131, v131, v157
	v_mul_f32_e32 v157, 0x3d922279, v129
	v_fmaak_f32 v157, v129, v157, 0x3fcc422a
	v_mul_f32_e32 v157, v129, v157
	v_mul_f32_e32 v157, 0xbfb8aa3b, v157
	v_exp_f32_e32 v157, v157
	v_cvt_pk_bf16_f32 v175, v130, v131
	v_cvt_pk_bf16_f32 v176, v154, v155
	s_nop 0
	v_add_f32_e32 v157, 1.0, v157
	v_rcp_f32_e32 v157, v157
	s_nop 0
	v_mul_f32_e32 v129, v129, v157
	v_cvt_pk_bf16_f32 v177, v128, v129
	global_store_dwordx4 v[152:153], v[174:177], off offset:256
	s_cbranch_vccnz .LBB0_825
	v_mul_f32_e32 v153, v168, v168
	v_fmac_f32_e32 v153, v149, v149
	v_mul_f32_e32 v149, v172, v172
	v_mul_f32_e32 v129, v129, v129
	v_fmac_f32_e32 v149, v170, v170
	v_fmac_f32_e32 v129, v128, v128
	v_mul_f32_e32 v128, v156, v156
	v_mul_f32_e32 v131, v131, v131
	v_add_f32_e32 v149, v153, v149
	v_mul_f32_e32 v153, v169, v169
	v_fmac_f32_e32 v128, v138, v138
	v_fmac_f32_e32 v131, v130, v130
	v_mul_f32_e32 v130, v155, v155
	v_mul_f32_e32 v152, v173, v173
	v_fmac_f32_e32 v153, v167, v167
	v_add_f32_e32 v128, v128, v131
	v_fmac_f32_e32 v130, v154, v154
	v_fmac_f32_e32 v152, v171, v171
	v_add_f32_e32 v149, v153, v149
	v_add_f32_e32 v128, v130, v128
	v_add_f32_e32 v149, v152, v149
	v_add_f32_e32 v128, v129, v128
	v_add_f32_e32 v128, v149, v128
	ds_bpermute_b32 v129, v162, v128
	s_waitcnt lgkmcnt(0)
	v_add_f32_e32 v128, v128, v129
	ds_bpermute_b32 v129, v163, v128
	s_and_saveexec_b64 s[0:1], s[4:5]
	s_cbranch_execz .LBB0_824
	v_lshl_add_u64 v[130:131], v[150:151], 2, s[68:69]
	s_waitcnt lgkmcnt(0)
	v_add_f32_e32 v128, v128, v129
	global_atomic_add_f32 v[130:131], v128, off

; __device__ __forceinline__ unsigned cvt_pk_bf16(float lo, float hi) { unsigned r; asm volatile("v_cvt_pk_bf16_f32 %0, %1, %2" : "=v"(r) : "v"(lo), "v"(hi)); return r; }
; __device__ __forceinline__ float rstd_of(float ss) { return __builtin_amdgcn_rsqf(ss * (1.0f / 2048.0f) + NORM_EPS); }
; __device__ __forceinline__ float gelu_tanh(float x) { const float u = x * (1.5957691216057308f + 0.0713548162726009f * x * x); return x * sigmoid_f(u); }
;     __device__ __forceinline__ void operator()(const f32x4 (&acc)[2][2][4][2], const Unit& u, int wr, int wc, int fr, int fq) const {
;     ...
;             for (int m = 0; m < 4; ++m) { bf16_t* rowp = base + (size_t)(ai * HALF + m * 16) * LD; const int grow = u.pm * BM + ai * HALF + m * 16 + rt; const float rs = rstd_of(ssin[grow]); float sq = 0.f;
; #pragma unroll
;                 for (int bj = 0; bj < 2; ++bj) { f32x4 v0 = acc[ai][bj][m][0] * rs, v1 = acc[ai][bj][m][1] * rs;
; #pragma unroll
;                     for (int j = 0; j < 4; ++j) { v0[j] = gelu_tanh(v0[j]); v1[j] = gelu_tanh(v1[j]); }
;                     sq += (v0[0] * v0[0] + v0[1] * v0[1]) + (v0[2] * v0[2] + v0[3] * v0[3]) + (v1[0] * v1[0] + v1[1] * v1[1]) + (v1[2] * v1[2] + v1[3] * v1[3]);
;                     u32x4 w; w.x = cvt_pk_bf16(v0[0], v0[1]); w.y = cvt_pk_bf16(v0[2], v0[3]); w.z = cvt_pk_bf16(v1[0], v1[1]); w.w = cvt_pk_bf16(v1[2], v1[3]);
;                     *(u32x4*)(rowp + bj * HALF) = w; }
.LBB0_825:
	v_or_b32_e32 v148, 48, v148
	v_ashrrev_i32_e32 v149, 31, v148
	s_waitcnt lgkmcnt(0)
	v_lshl_add_u64 v[128:129], v[148:149], 2, s[66:67]
	v_mov_b32_e32 v128, v233
	s_mov_b32 s0, 0xb0000
	v_add_co_u32_e32 v146, vcc, s0, v146
	v_fmamk_f32 v128, v128, 0x3a000000, v166
	v_rsq_f32_e32 v138, v128
	v_addc_co_u32_e32 v147, vcc, 0, v147, vcc
	s_and_b64 vcc, exec, s[6:7]
	v_pk_mul_f32 v[130:131], v[36:37], v[138:139] op_sel_hi:[1,0]
	v_pk_mul_f32 v[152:153], v[32:33], v[138:139] op_sel_hi:[1,0]
	v_mul_f32_e32 v154, 0x3d922279, v130
	v_fmaak_f32 v154, v130, v154, 0x3fcc422a
	v_mul_f32_e32 v154, v130, v154
	v_mul_f32_e32 v154, 0xbfb8aa3b, v154
	v_exp_f32_e32 v154, v154
	v_pk_mul_f32 v[128:129], v[38:39], v[138:139] op_sel_hi:[1,0]
	v_pk_mul_f32 v[150:151], v[34:35], v[138:139] op_sel_hi:[1,0]
	v_add_f32_e32 v154, 1.0, v154
	v_rcp_f32_e32 v154, v154
	s_nop 0
	v_mul_f32_e32 v154, v130, v154
	v_mul_f32_e32 v130, 0x3d922279, v152
	v_fmaak_f32 v130, v152, v130, 0x3fcc422a
	v_mul_f32_e32 v130, v152, v130
	v_mul_f32_e32 v130, 0xbfb8aa3b, v130
	v_exp_f32_e32 v130, v130
	s_nop 0
	v_add_f32_e32 v130, 1.0, v130
	v_rcp_f32_e32 v130, v130
	s_nop 0
	v_mul_f32_e32 v155, v152, v130
	v_mul_f32_e32 v130, 0x3d922279, v131
	v_fmaak_f32 v130, v131, v130, 0x3fcc422a
	v_mul_f32_e32 v130, v131, v130
	v_mul_f32_e32 v130, 0xbfb8aa3b, v130
	v_exp_f32_e32 v130, v130
	s_nop 0
	v_add_f32_e32 v130, 1.0, v130
	v_rcp_f32_e32 v130, v130
	s_nop 0
	v_mul_f32_e32 v156, v131, v130
	v_mul_f32_e32 v130, 0x3d922279, v153
	v_fmaak_f32 v130, v153, v130, 0x3fcc422a
	v_mul_f32_e32 v130, v153, v130
	v_mul_f32_e32 v130, 0xbfb8aa3b, v130
	v_exp_f32_e32 v130, v130
	s_nop 0
	v_add_f32_e32 v130, 1.0, v130
	v_rcp_f32_e32 v130, v130
	s_nop 0
	v_mul_f32_e32 v157, v153, v130
	v_mul_f32_e32 v130, 0x3d922279, v128
	v_fmaak_f32 v130, v128, v130, 0x3fcc422a
	v_mul_f32_e32 v130, v128, v130
	v_mul_f32_e32 v130, 0xbfb8aa3b, v130
	v_exp_f32_e32 v130, v130
	v_pk_mul_f32 v[152:153], v[4:5], v[138:139] op_sel_hi:[1,0]
	v_add_f32_e32 v130, 1.0, v130
	v_rcp_f32_e32 v130, v130
	s_nop 0
	v_mul_f32_e32 v167, v128, v130
	v_mul_f32_e32 v128, 0x3d922279, v150
	v_fmaak_f32 v128, v150, v128, 0x3fcc422a
	v_mul_f32_e32 v128, v150, v128
	v_mul_f32_e32 v128, 0xbfb8aa3b, v128
	v_exp_f32_e32 v128, v128
	s_nop 0
	v_add_f32_e32 v128, 1.0, v128
	v_rcp_f32_e32 v128, v128
	s_nop 0
	v_mul_f32_e32 v168, v150, v128
	v_mul_f32_e32 v128, 0x3d922279, v129
	v_fmaak_f32 v128, v129, v128, 0x3fcc422a
	v_mul_f32_e32 v128, v129, v128
	v_mul_f32_e32 v128, 0xbfb8aa3b, v128
	v_exp_f32_e32 v128, v128
	s_nop 0
	v_add_f32_e32 v128, 1.0, v128
	v_rcp_f32_e32 v128, v128
	s_nop 0
	v_mul_f32_e32 v169, v129, v128
	v_mul_f32_e32 v128, 0x3d922279, v151
	v_fmaak_f32 v128, v151, v128, 0x3fcc422a
	v_mul_f32_e32 v128, v151, v128
	v_mul_f32_e32 v128, 0xbfb8aa3b, v128
	v_exp_f32_e32 v128, v128
	s_nop 0
	v_add_f32_e32 v128, 1.0, v128
	v_rcp_f32_e32 v128, v128
	s_nop 0
	v_mul_f32_e32 v170, v151, v128
	v_cvt_pk_bf16_f32 v128, v154, v156
	v_cvt_pk_bf16_f32 v129, v167, v169
	v_cvt_pk_bf16_f32 v130, v155, v157
	v_cvt_pk_bf16_f32 v131, v168, v170
	global_store_dwordx4 v[146:147], v[128:131], off
	v_pk_mul_f32 v[150:151], v[0:1], v[138:139] op_sel_hi:[1,0]
	s_nop 0
	v_pk_mul_f32 v[130:131], v[6:7], v[138:139] op_sel_hi:[1,0]
	v_pk_mul_f32 v[128:129], v[2:3], v[138:139] op_sel_hi:[1,0]
	v_mul_f32_e32 v138, 0x3d922279, v152
	v_fmaak_f32 v138, v152, v138, 0x3fcc422a
	v_mul_f32_e32 v138, v152, v138
	v_mul_f32_e32 v138, 0xbfb8aa3b, v138
	v_exp_f32_e32 v138, v138
	s_nop 0
	v_add_f32_e32 v138, 1.0, v138
	v_rcp_f32_e32 v138, v138
	s_nop 0
	v_mul_f32_e32 v138, v152, v138
	v_mul_f32_e32 v152, 0x3d922279, v150
	v_fmaak_f32 v152, v150, v152, 0x3fcc422a
	v_mul_f32_e32 v152, v150, v152
	v_mul_f32_e32 v152, 0xbfb8aa3b, v152
	v_exp_f32_e32 v152, v152
	s_nop 0
	v_add_f32_e32 v152, 1.0, v152
	v_rcp_f32_e32 v152, v152
	s_nop 0
	v_mul_f32_e32 v150, v150, v152
	v_mul_f32_e32 v152, 0x3d922279, v153
	v_fmaak_f32 v152, v153, v152, 0x3fcc422a
	v_mul_f32_e32 v152, v153, v152
	v_mul_f32_e32 v152, 0xbfb8aa3b, v152
	v_exp_f32_e32 v152, v152
	s_nop 0
	v_add_f32_e32 v152, 1.0, v152
	v_rcp_f32_e32 v152, v152
	s_nop 0
	v_mul_f32_e32 v152, v153, v152
	v_mul_f32_e32 v153, 0x3d922279, v151
	v_fmaak_f32 v153, v151, v153, 0x3fcc422a
	v_mul_f32_e32 v153, v151, v153
	v_mul_f32_e32 v153, 0xbfb8aa3b, v153
	v_exp_f32_e32 v153, v153
	v_cvt_pk_bf16_f32 v172, v138, v152
	s_nop 0
	v_add_f32_e32 v153, 1.0, v153
	v_rcp_f32_e32 v153, v153
	s_nop 0
	v_mul_f32_e32 v151, v151, v153
	v_mul_f32_e32 v153, 0x3d922279, v130
	v_fmaak_f32 v153, v130, v153, 0x3fcc422a
	v_mul_f32_e32 v153, v130, v153
	v_mul_f32_e32 v153, 0xbfb8aa3b, v153
	v_exp_f32_e32 v153, v153
	s_nop 0
	v_add_f32_e32 v153, 1.0, v153
	v_rcp_f32_e32 v153, v153
	s_nop 0
	v_mul_f32_e32 v130, v130, v153
	v_mul_f32_e32 v153, 0x3d922279, v128
	v_fmaak_f32 v153, v128, v153, 0x3fcc422a
	v_mul_f32_e32 v153, v128, v153
	v_mul_f32_e32 v153, 0xbfb8aa3b, v153
	v_exp_f32_e32 v153, v153
	s_nop 0
	v_add_f32_e32 v153, 1.0, v153
	v_rcp_f32_e32 v153, v153
	s_nop 0
	v_mul_f32_e32 v128, v128, v153
	v_mul_f32_e32 v153, 0x3d922279, v131
	v_fmaak_f32 v153, v131, v153, 0x3fcc422a
	v_mul_f32_e32 v153, v131, v153
	v_mul_f32_e32 v153, 0xbfb8aa3b, v153
	v_exp_f32_e32 v153, v153
	s_nop 0
	v_add_f32_e32 v153, 1.0, v153
	v_rcp_f32_e32 v153, v153
	s_nop 0
	v_mul_f32_e32 v131, v131, v153
	v_mul_f32_e32 v153, 0x3d922279, v129
	v_fmaak_f32 v153, v129, v153, 0x3fcc422a
	v_mul_f32_e32 v153, v129, v153
	v_mul_f32_e32 v153, 0xbfb8aa3b, v153
	v_exp_f32_e32 v153, v153
	v_cvt_pk_bf16_f32 v173, v130, v131
	v_cvt_pk_bf16_f32 v174, v150, v151
	s_nop 0
	v_add_f32_e32 v153, 1.0, v153
	v_rcp_f32_e32 v153, v153
	s_nop 0
	v_mul_f32_e32 v129, v129, v153
	v_cvt_pk_bf16_f32 v175, v128, v129
	global_store_dwordx4 v[146:147], v[172:175], off offset:256
	s_cbranch_vccz .LBB0_827
	s_andn2_b64 vcc, exec, s[96:97]
	s_cbranch_vccnz .LBB0_767
	s_branch .LBB0_830
